# v032 + first K-fragment LDS reads of each QK segment issued early inside the preceding scale/exp stretch
# baseline (speedup 1.0000x reference)
.LBB0_449:
	s_lshl_b32 s0, s38, 1
	s_and_b32 s0, s0, 14
	s_ashr_i32 s34, s38, 7
	s_add_i32 s56, s0, s34
	s_ashr_i32 s57, s56, 31
	s_lshl_b32 s0, s38, 5
	s_lshl_b64 s[2:3], s[56:57], 12
	s_and_b32 s39, s0, 0xf00
	s_or_b32 s0, s2, s39
	s_mul_i32 s2, s3, 0x180
	s_mul_hi_u32 s3, s0, 0x180
	s_and_b32 s1, s21, 14
	s_add_i32 s3, s3, s2
	s_mulk_i32 s0, 0x180
	v_mov_b32_e32 v68, v166
	s_add_u32 s40, s7, s0
	s_addc_u32 s41, s14, s3
	v_ashrrev_i32_e32 v2, 6, v68
	s_mul_i32 s2, s56, 0x198000
	v_and_b32_e32 v168, 31, v68
	v_lshlrev_b32_e32 v150, 5, v2
	s_mul_hi_i32 s0, s56, 0x198000
	s_add_u32 s4, s15, s2
	v_bfe_u32 v169, v68, 5, 1
	v_or_b32_e32 v3, v150, v168
	v_mov_b64_e32 v[0:1], s[40:41]
	s_addc_u32 s5, s16, s0
	s_mul_i32 s2, s56, 0x110000
	v_mad_i64_i32 v[0:1], s[40:41], v3, s29, v[0:1]
	v_lshlrev_b32_e32 v152, 4, v169
	v_mov_b32_e32 v153, v149
	s_mul_hi_i32 s0, s56, 0x110000
	s_add_u32 s2, s17, s2
	v_lshl_add_u64 v[0:1], v[0:1], 0, v[152:153]
	s_addc_u32 s3, s20, s0
	global_load_dwordx4 v[140:143], v[0:1], off
	global_load_dwordx4 v[136:139], v[0:1], off offset:32
	global_load_dwordx4 v[132:135], v[0:1], off offset:64
	global_load_dwordx4 v[128:131], v[0:1], off offset:96
	global_load_dwordx4 v[124:127], v[0:1], off offset:128
	global_load_dwordx4 v[120:123], v[0:1], off offset:160
	global_load_dwordx4 v[116:119], v[0:1], off offset:192
	global_load_dwordx4 v[112:115], v[0:1], off offset:224
	global_load_dwordx4 v[108:111], v[0:1], off offset:256
	global_load_dwordx4 v[104:107], v[0:1], off offset:288
	global_load_dwordx4 v[100:103], v[0:1], off offset:320
	global_load_dwordx4 v[96:99], v[0:1], off offset:352
	v_readfirstlane_b32 s0, v2
	v_mov_b32_e32 v0, v166
	s_lshl_b32 s40, s0, 10
	s_cmp_lg_u32 0, -1
	v_mul_hi_i32 v1, v0, s31
	v_lshrrev_b32_e32 v2, 31, v1
	v_ashrrev_i32_e32 v1, 2, v1
	s_cselect_b32 s41, 0, 0
	v_add_u32_e32 v1, v1, v2
	s_add_i32 s41, s41, s40
	v_mul_lo_u32 v2, v1, s33
	v_mul_lo_u32 v3, v1, s29
	v_lshlrev_b32_e32 v1, 3, v1
	s_add_i32 s42, s41, 0xc000
	v_add_lshl_u32 v2, v2, v0, 4
	v_and_b32_e32 v1, 0x70, v1
	v_xad_u32 v1, v2, v1, v3
	s_mov_b32 m0, s42
	s_add_i32 s43, s41, 0xe000
	v_mov_b32_e32 v203, v1
	global_load_lds_dwordx4 v1, s[4:5]
	v_add_u32_e32 v1, 0x200, v0
	v_mul_hi_i32 v2, v1, s31
	v_lshrrev_b32_e32 v3, 31, v2
	v_ashrrev_i32_e32 v2, 2, v2
	v_add_u32_e32 v2, v2, v3
	v_mul_lo_u32 v3, v2, s33
	v_add_lshl_u32 v1, v3, v1, 4
	v_mul_lo_u32 v3, v2, s29
	v_lshlrev_b32_e32 v2, 3, v2
	v_and_b32_e32 v2, 0x70, v2
	v_xad_u32 v1, v1, v2, v3
	s_mov_b32 m0, s43
	s_mov_b32 s68, 0
	v_mov_b32_e32 v204, v1
	global_load_lds_dwordx4 v1, s[4:5]
	v_add_u32_e32 v1, 0x400, v0
	v_mul_hi_i32 v2, v1, s31
	v_lshrrev_b32_e32 v3, 31, v2
	v_ashrrev_i32_e32 v2, 2, v2
	v_add_u32_e32 v2, v2, v3
	v_mul_lo_u32 v3, v2, s33
	v_add_lshl_u32 v1, v3, v1, 4
	v_mul_lo_u32 v3, v2, s29
	v_lshlrev_b32_e32 v2, 3, v2
	v_and_b32_e32 v2, 0x70, v2
	v_xad_u32 v1, v1, v2, v3
	s_add_i32 m0, s41, 0x10000
	v_bfe_u32 v2, v0, 2, 2
	v_lshrrev_b32_e32 v3, 1, v0
	v_mov_b32_e32 v205, v1
	global_load_lds_dwordx4 v1, s[4:5]
	v_lshlrev_b32_e32 v1, 4, v0
	v_and_or_b32 v2, v3, 8, v2
	v_lshlrev_b32_e32 v3, 1, v0
	v_bfe_i32 v0, v0, 4, 24
	v_and_b32_e32 v4, 0xfffff0, v0
	v_lshrrev_b32_e32 v0, 1, v0
	v_and_b32_e32 v3, 0xc0, v3
	v_and_b32_e32 v0, 4, v0
	v_and_or_b32 v3, v1, 48, v3
	v_or3_b32 v0, v4, v0, v2
	v_lshl_or_b32 v0, v0, 8, v3
	s_mov_b32 m0, s41
	s_mov_b32 s69, s68
	v_mov_b32_e32 v206, v0
	global_load_lds_dwordx4 v0, s[2:3]
	v_add_u32_e32 v0, 0x2000, v1
	v_ashrrev_i32_e32 v0, 8, v0
	v_and_b32_e32 v1, 0xfffff0, v0
	v_lshrrev_b32_e32 v0, 1, v0
	v_and_b32_e32 v0, 4, v0
	v_or3_b32 v0, v1, v0, v2
	v_lshl_or_b32 v0, v0, 8, v3
	s_add_i32 m0, s41, 0x2000
	s_add_u32 s4, s4, 0x6000
	v_mov_b32_e32 v207, v0
	global_load_lds_dwordx4 v0, s[2:3]
	v_mov_b32_e32 v0, v166
	s_waitcnt vmcnt(0)
	s_waitcnt vmcnt(0) lgkmcnt(0)
	s_barrier
	s_addc_u32 s5, s5, 0
	v_mul_hi_i32 v1, v0, s31
	v_lshrrev_b32_e32 v2, 31, v1
	v_ashrrev_i32_e32 v1, 2, v1
	v_add_u32_e32 v1, v1, v2
	v_mul_lo_u32 v2, v1, s33
	v_mul_lo_u32 v3, v1, s29
	v_lshlrev_b32_e32 v1, 3, v1
	v_add_lshl_u32 v2, v2, v0, 4
	v_and_b32_e32 v1, 0x70, v1
	s_add_i32 m0, s41, 0x12000
	v_xad_u32 v1, v2, v1, v3
	global_load_lds_dwordx4 v1, s[4:5]
	v_add_u32_e32 v1, 0x200, v0
	v_mul_hi_i32 v2, v1, s31
	v_lshrrev_b32_e32 v3, 31, v2
	v_ashrrev_i32_e32 v2, 2, v2
	v_add_u32_e32 v2, v2, v3
	v_mul_lo_u32 v3, v2, s33
	v_add_lshl_u32 v1, v3, v1, 4
	v_mul_lo_u32 v3, v2, s29
	v_lshlrev_b32_e32 v2, 3, v2
	v_and_b32_e32 v2, 0x70, v2
	v_xad_u32 v1, v1, v2, v3
	s_add_i32 m0, s41, 0x14000
	s_mov_b32 s70, s68
	global_load_lds_dwordx4 v1, s[4:5]
	v_add_u32_e32 v1, 0x400, v0
	v_mul_hi_i32 v2, v1, s31
	v_lshrrev_b32_e32 v3, 31, v2
	v_ashrrev_i32_e32 v2, 2, v2
	v_add_u32_e32 v2, v2, v3
	v_mul_lo_u32 v3, v2, s33
	v_add_lshl_u32 v1, v3, v1, 4
	v_mul_lo_u32 v3, v2, s29
	v_lshlrev_b32_e32 v2, 3, v2
	v_and_b32_e32 v2, 0x70, v2
	v_xad_u32 v1, v1, v2, v3
	s_add_i32 m0, s41, 0x16000
	v_bfe_u32 v2, v0, 2, 2
	v_lshrrev_b32_e32 v3, 1, v0
	global_load_lds_dwordx4 v1, s[4:5]
	v_lshlrev_b32_e32 v1, 4, v0
	v_and_or_b32 v2, v3, 8, v2
	v_lshlrev_b32_e32 v3, 1, v0
	v_bfe_i32 v0, v0, 4, 24
	v_and_b32_e32 v4, 0xfffff0, v0
	v_lshrrev_b32_e32 v0, 1, v0
	v_and_b32_e32 v3, 0xc0, v3
	v_and_b32_e32 v0, 4, v0
	s_add_u32 s2, s2, 0x4000
	v_and_or_b32 v3, v1, 48, v3
	v_or3_b32 v0, v4, v0, v2
	s_addc_u32 s3, s3, 0
	s_add_i32 m0, s41, 0x4000
	v_lshl_or_b32 v0, v0, 8, v3
	global_load_lds_dwordx4 v0, s[2:3]
	v_add_u32_e32 v0, 0x2000, v1
	v_ashrrev_i32_e32 v0, 8, v0
	v_and_b32_e32 v1, 0xfffff0, v0
	v_lshrrev_b32_e32 v0, 1, v0
	v_and_b32_e32 v0, 4, v0
	v_or3_b32 v0, v1, v0, v2
	v_lshl_or_b32 v0, v0, 8, v3
	s_add_i32 m0, s41, 0x6000
	s_mov_b32 s71, s68
	global_load_lds_dwordx4 v0, s[2:3]
	v_mov_b32_e32 v0, v166
	s_mov_b32 s72, s68
	v_and_b32_e32 v1, 31, v0
	v_lshlrev_b32_e32 v2, 3, v0
	v_lshrrev_b32_e32 v0, 1, v0
	v_and_b32_e32 v56, 0x70, v2
	v_mad_u32_u24 v57, v1, s29, 0
	v_and_b32_e32 v58, 16, v0
	v_xad_u32 v69, v58, v56, v57
	ds_read_b128 v[0:3], v69 offset:49152
	ds_read_b128 v[4:7], v69 offset:49280
	s_waitcnt lgkmcnt(0)
	v_mfma_f32_32x32x16_bf16 v[16:31], v[0:3], v[140:143], 0
	ds_read_b128 v[0:3], v69 offset:61440
	v_or_b32_e32 v8, 32, v58
	v_xad_u32 v70, v8, v56, v57
	ds_read_b128 v[8:11], v69 offset:49408
	v_or_b32_e32 v48, 64, v58
	v_xad_u32 v71, v48, v56, v57
	v_or_b32_e32 v58, 0x60, v58
	s_waitcnt lgkmcnt(0)
	v_mfma_f32_32x32x16_bf16 v[32:47], v[0:3], v[140:143], 0
	ds_read_b128 v[0:3], v70 offset:49152
	ds_read_b128 v[12:15], v70 offset:49280
	ds_read_b128 v[48:51], v70 offset:49408
	v_xad_u32 v72, v58, v56, v57
	s_mov_b32 s73, s68
	s_mov_b32 s74, s68
	s_mov_b32 s75, s68
	s_mov_b32 s76, s68
	s_waitcnt lgkmcnt(0)
	v_mfma_f32_32x32x16_bf16 v[16:31], v[0:3], v[136:139], v[16:31]
	ds_read_b128 v[0:3], v70 offset:61440
	s_mov_b32 s77, s68
	s_mov_b32 s78, s68
	s_mov_b32 s79, s68
	s_mov_b32 s80, s68
	s_mov_b32 s81, s68
	s_mov_b32 s82, s68
	s_waitcnt lgkmcnt(0)
	v_mfma_f32_32x32x16_bf16 v[32:47], v[0:3], v[136:139], v[32:47]
	ds_read_b128 v[0:3], v71 offset:49152
	ds_read_b128 v[52:55], v71 offset:49280
	ds_read_b128 v[56:59], v71 offset:49408
	s_mov_b32 s83, s68
	s_mov_b32 s0, -1
	v_cmp_eq_u32_e64 s[2:3], 0, v169
	s_movk_i32 s49, 0x4000
	s_mov_b32 s50, 0x8000
	s_waitcnt lgkmcnt(0)
	v_mfma_f32_32x32x16_bf16 v[16:31], v[0:3], v[132:135], v[16:31]
	ds_read_b128 v[0:3], v71 offset:61440
	v_mov_b32_e32 v170, v149
	s_waitcnt lgkmcnt(0)
	v_mfma_f32_32x32x16_bf16 v[32:47], v[0:3], v[132:135], v[32:47]
	ds_read_b128 v[0:3], v72 offset:49152
	ds_read_b128 v[60:63], v72 offset:49280
	s_waitcnt lgkmcnt(0)
	v_mfma_f32_32x32x16_bf16 v[16:31], v[0:3], v[128:131], v[16:31]
	ds_read_b128 v[0:3], v72 offset:61440
	ds_read_b128 v[64:67], v72 offset:49408
	v_mfma_f32_32x32x16_bf16 v[16:31], v[4:7], v[124:127], v[16:31]
	s_waitcnt lgkmcnt(0)
	v_mfma_f32_32x32x16_bf16 v[32:47], v[0:3], v[128:131], v[32:47]
	ds_read_b128 v[0:3], v69 offset:61568
	ds_read_b128 v[4:7], v69 offset:61696
	v_mfma_f32_32x32x16_bf16 v[16:31], v[12:15], v[120:123], v[16:31]
	s_waitcnt lgkmcnt(0)
	v_mfma_f32_32x32x16_bf16 v[32:47], v[0:3], v[124:127], v[32:47]
	ds_read_b128 v[0:3], v70 offset:61568
	ds_read_b128 v[12:15], v70 offset:61696
	v_mfma_f32_32x32x16_bf16 v[16:31], v[52:55], v[116:119], v[16:31]
	s_waitcnt lgkmcnt(0)
	v_mfma_f32_32x32x16_bf16 v[32:47], v[0:3], v[120:123], v[32:47]
	ds_read_b128 v[0:3], v71 offset:61568
	ds_read_b128 v[52:55], v71 offset:61696
	v_mfma_f32_32x32x16_bf16 v[16:31], v[60:63], v[112:115], v[16:31]
	s_waitcnt lgkmcnt(0)
	v_mfma_f32_32x32x16_bf16 v[32:47], v[0:3], v[116:119], v[32:47]
	ds_read_b128 v[0:3], v72 offset:61568
	ds_read_b128 v[60:63], v72 offset:61696
	s_waitcnt vmcnt(0)
	s_waitcnt vmcnt(0) lgkmcnt(0)
	s_barrier
	v_mfma_f32_32x32x16_bf16 v[16:31], v[8:11], v[108:111], v[16:31]
	v_mfma_f32_32x32x16_bf16 v[32:47], v[0:3], v[112:115], v[32:47]
	v_and_b32_e32 v0, 0x3fffffc0, v68
	v_lshl_add_u32 v151, v0, 2, s30
	v_lshl_add_u32 v153, v168, 2, v151
	v_mfma_f32_32x32x16_bf16 v[16:31], v[48:51], v[104:107], v[16:31]
	v_mfma_f32_32x32x16_bf16 v[32:47], v[4:7], v[108:111], v[32:47]
	v_mfma_f32_32x32x16_bf16 v[16:31], v[56:59], v[100:103], v[16:31]
	v_mfma_f32_32x32x16_bf16 v[32:47], v[12:15], v[104:107], v[32:47]
	v_mov_b64_e32 v[0:1], s[68:69]
	v_mov_b64_e32 v[14:15], s[82:83]
	v_mov_b64_e32 v[2:3], s[70:71]
	v_mov_b64_e32 v[4:5], s[72:73]
	v_mov_b64_e32 v[6:7], s[74:75]
	v_mov_b64_e32 v[8:9], s[76:77]
	v_mov_b64_e32 v[10:11], s[78:79]
	v_mfma_f32_32x32x16_bf16 v[16:31], v[64:67], v[96:99], v[16:31]
	v_mov_b64_e32 v[12:13], s[80:81]
	v_mfma_f32_32x32x16_bf16 v[32:47], v[52:55], v[100:103], v[32:47]
	s_nop 9
	v_max_f32_e32 v48, v17, v17
	v_max_f32_e32 v49, v16, v16
	v_max_f32_e32 v48, v49, v48
	v_max3_f32 v48, v48, v18, v19
	v_max3_f32 v48, v48, v20, v21
	v_max3_f32 v48, v48, v22, v23
	v_max3_f32 v48, v48, v24, v25
	v_mfma_f32_32x32x16_bf16 v[32:47], v[60:63], v[96:99], v[32:47]
	v_max3_f32 v48, v48, v26, v27
	v_max3_f32 v48, v48, v28, v29
	v_max3_f32 v48, v48, v30, v31
	s_nop 8
	v_max3_f32 v48, v48, v32, v33
	v_max3_f32 v48, v48, v34, v35
	v_max3_f32 v48, v48, v36, v37
	v_max3_f32 v48, v48, v38, v39
	v_max3_f32 v48, v48, v40, v41
	v_max3_f32 v48, v48, v42, v43
	v_max3_f32 v48, v48, v44, v45
	v_max3_f32 v48, v48, v46, v47
	v_mov_b32_e32 v49, v48
	s_nop 1
	v_permlane32_swap_b32_e32 v48, v49
	v_max_f32_e32 v49, v49, v49
	v_max_f32_e32 v48, v48, v48
	v_max_f32_e32 v48, v48, v49
	v_add_f32_e32 v49, 0x7149f2ca, v48
	v_cmp_ge_f32_e32 vcc, s37, v49
	s_cmp_eq_u64 vcc, exec
	v_max_f32_e32 v48, 0xf149f2ca, v48
	s_cselect_b64 vcc, -1, 0
	v_cndmask_b32_e32 v172, v48, v167, vcc
	v_sub_f32_e32 v49, 0xf149f2ca, v48
	v_mul_f32_e32 v48, 0xbdd53b94, v172
	v_fmamk_f32 v16, v16, 0x3dd53b94, v48
	v_exp_f32_e32 v186, v16
	v_fmamk_f32 v16, v17, 0x3dd53b94, v48
	v_exp_f32_e32 v189, v16
	v_fmamk_f32 v16, v18, 0x3dd53b94, v48
	v_exp_f32_e32 v187, v16
	v_fmamk_f32 v16, v19, 0x3dd53b94, v48
	v_exp_f32_e32 v190, v16
	v_fmamk_f32 v16, v20, 0x3dd53b94, v48
	v_exp_f32_e32 v188, v16
	v_fmamk_f32 v16, v21, 0x3dd53b94, v48
	v_exp_f32_e32 v191, v16
	v_fmamk_f32 v16, v22, 0x3dd53b94, v48
	v_exp_f32_e32 v184, v16
	v_fmamk_f32 v16, v23, 0x3dd53b94, v48
	v_exp_f32_e32 v185, v16
	v_fmamk_f32 v16, v24, 0x3dd53b94, v48
	v_mul_f32_e32 v49, 0x3dd53b94, v49
	v_exp_f32_e32 v180, v16
	v_fmamk_f32 v16, v25, 0x3dd53b94, v48
	v_exp_f32_e32 v49, v49
	v_exp_f32_e32 v182, v16
	v_fmamk_f32 v16, v26, 0x3dd53b94, v48
	v_exp_f32_e32 v181, v16
	v_fmamk_f32 v16, v27, 0x3dd53b94, v48
	v_exp_f32_e32 v183, v16
	v_fmamk_f32 v16, v28, 0x3dd53b94, v48
	v_exp_f32_e32 v176, v16
	v_fmamk_f32 v16, v29, 0x3dd53b94, v48
	s_add_i32 s4, s34, s1
	v_pk_fma_f32 v[144:145], v[46:47], s[6:7], v[48:49] op_sel_hi:[1,0,0]
	v_pk_fma_f32 v[156:157], v[44:45], s[6:7], v[48:49] op_sel_hi:[1,0,0]
	v_pk_fma_f32 v[160:161], v[42:43], s[6:7], v[48:49] op_sel_hi:[1,0,0]
	v_pk_fma_f32 v[146:147], v[40:41], s[6:7], v[48:49] op_sel_hi:[1,0,0]
	v_pk_fma_f32 v[154:155], v[38:39], s[6:7], v[48:49] op_sel_hi:[1,0,0]
	v_pk_fma_f32 v[158:159], v[36:37], s[6:7], v[48:49] op_sel_hi:[1,0,0]
	v_pk_fma_f32 v[162:163], v[34:35], s[6:7], v[48:49] op_sel_hi:[1,0,0]
	v_pk_fma_f32 v[164:165], v[32:33], s[6:7], v[48:49] op_sel_hi:[1,0,0]
	v_exp_f32_e32 v178, v16
	v_fmamk_f32 v16, v30, 0x3dd53b94, v48
	v_fmac_f32_e32 v48, 0x3dd53b94, v31
	s_mul_i32 s1, s4, 0x110000
	v_exp_f32_e32 v177, v16
	v_exp_f32_e32 v179, v48
	s_mul_hi_i32 s5, s4, 0x110000
	s_add_u32 s1, s86, s1
	s_addc_u32 s45, s87, s5
	s_mul_hi_i32 s5, s4, 0x198000
	s_mul_i32 s4, s4, 0x198000
	v_cndmask_b32_e64 v171, v49, 1.0, vcc
	s_add_u32 s46, s86, s4
	v_mov_b64_e32 v[62:63], v[14:15]
	v_mov_b64_e32 v[46:47], v[14:15]
	v_mov_b64_e32 v[30:31], v[14:15]
	s_addc_u32 s47, s87, s5
	s_add_i32 s48, s42, 0x4000
	v_mov_b64_e32 v[60:61], v[12:13]
	v_mov_b64_e32 v[58:59], v[10:11]
	v_mov_b64_e32 v[56:57], v[8:9]
	v_mov_b64_e32 v[54:55], v[6:7]
	v_mov_b64_e32 v[52:53], v[4:5]
	v_mov_b64_e32 v[50:51], v[2:3]
	v_mov_b64_e32 v[48:49], v[0:1]
	v_mov_b64_e32 v[44:45], v[12:13]
	v_mov_b64_e32 v[42:43], v[10:11]
	v_mov_b64_e32 v[40:41], v[8:9]
	v_mov_b64_e32 v[38:39], v[6:7]
	v_mov_b64_e32 v[36:37], v[4:5]
	v_mov_b64_e32 v[34:35], v[2:3]
	v_mov_b64_e32 v[32:33], v[0:1]
	v_mov_b64_e32 v[28:29], v[12:13]
	v_mov_b64_e32 v[26:27], v[10:11]
	v_mov_b64_e32 v[24:25], v[8:9]
	v_mov_b64_e32 v[22:23], v[6:7]
	v_mov_b64_e32 v[20:21], v[4:5]
	v_mov_b64_e32 v[18:19], v[2:3]
	v_mov_b64_e32 v[16:17], v[0:1]
	v_and_b32_e32 v65, 31, v166
	v_lshlrev_b32_e32 v66, 3, v166
	v_and_b32_e32 v66, 0x70, v66
	v_lshrrev_b32_e32 v64, 1, v166
	v_and_b32_e32 v64, 16, v64
	s_movk_i32 s98, 0x6000
	v_mov_b32_e32 v67, s98
	v_mad_u32_u24 v65, v65, s29, v67
	v_xad_u32 v208, v64, v66, v65
	v_or_b32_e32 v67, 32, v64
	v_xad_u32 v209, v67, v66, v65
	v_or_b32_e32 v67, 64, v64
	v_xad_u32 v210, v67, v66, v65
	v_or_b32_e32 v67, 0x60, v64
	v_xad_u32 v211, v67, v66, v65
	v_lshlrev_b32_e32 v64, 3, v166
	v_lshlrev_b32_e32 v65, 4, v166
	v_lshlrev_b32_e32 v66, 1, v166
	v_and_b32_e32 v67, 24, v64
	v_and_b32_e32 v65, 0xc0, v65
	v_and_b32_e32 v66, 32, v66
	v_or3_b32 v66, v67, v65, v66
	v_and_b32_e32 v64, 0x100, v64
	v_add_u32_e32 v212, v64, v66
	ds_read_b128 v[64:67], v208 offset:49152
	ds_read_b128 v[68:71], v208 offset:61440
	ds_read_b128 v[222:225], v209 offset:49152
	ds_read_b128 v[226:229], v209 offset:61440
	ds_read_b128 v[230:233], v210 offset:49152
	ds_read_b128 v[234:237], v210 offset:61440
.LBB0_450:
	s_add_u32 s34, s46, s22
	s_addc_u32 s35, s47, s23
	s_mov_b32 m0, s42
	s_add_u32 s98, s34, s24
	s_addc_u32 s99, s35, s25
	global_load_lds_dwordx4 v203, s[98:99]
	s_mov_b32 m0, s43
	s_add_i32 s4, s41, s50
	global_load_lds_dwordx4 v204, s[98:99]
	s_mov_b32 m0, s48
	s_nop 0
	global_load_lds_dwordx4 v205, s[98:99]
	s_add_u32 s58, s1, s22
	s_addc_u32 s59, s45, s23
	s_mov_b32 m0, s4
	s_mov_b32 s51, s49
	s_add_u32 s100, s58, s26
	s_addc_u32 s101, s59, s27
	global_load_lds_dwordx4 v206, s[100:101]
	s_add_i32 m0, s4, 0x2000
	s_mov_b32 s49, s68
	global_load_lds_dwordx4 v207, s[100:101]
	s_add_i32 s57, 0, 0x12000
	s_waitcnt lgkmcnt(4)
	v_mfma_f32_32x32x16_bf16 v[80:95], v[64:67], v[140:143], 0
	v_exp_f32_e32 v200, v144
	v_mfma_f32_32x32x16_bf16 v[64:79], v[68:71], v[140:143], 0
	v_add_f32_e32 v238, v186, v188
	ds_read_b128 v[214:217], v211 offset:49152
	ds_read_b128 v[218:221], v211 offset:61440
	s_waitcnt lgkmcnt(4)
	v_mfma_f32_32x32x16_bf16 v[80:95], v[222:225], v[136:139], v[80:95]
	v_add_f32_e32 v239, v189, v191
	v_add_f32_e32 v240, v187, v184
	v_add_f32_e32 v241, v190, v185
	v_mfma_f32_32x32x16_bf16 v[64:79], v[226:229], v[136:139], v[64:79]
	v_add_f32_e32 v238, v180, v238
	v_add_f32_e32 v239, v182, v239
	v_add_f32_e32 v240, v181, v240
	ds_read_b128 v[222:225], v208 offset:49280
	ds_read_b128 v[226:229], v208 offset:61568
	s_waitcnt lgkmcnt(4)
	v_mfma_f32_32x32x16_bf16 v[80:95], v[230:233], v[132:135], v[80:95]
	v_add_f32_e32 v241, v183, v241
	v_add_f32_e32 v238, v176, v238
	v_add_f32_e32 v239, v178, v239
	v_mfma_f32_32x32x16_bf16 v[64:79], v[234:237], v[132:135], v[64:79]
	v_exp_f32_e32 v162, v162
	v_add_f32_e32 v240, v177, v240
	v_exp_f32_e32 v163, v163
	v_add_f32_e32 v241, v179, v241
	ds_read_b128 v[230:233], v209 offset:49280
	ds_read_b128 v[234:237], v209 offset:61568
	s_waitcnt lgkmcnt(4)
	v_mfma_f32_32x32x16_bf16 v[80:95], v[214:217], v[128:131], v[80:95]
	v_exp_f32_e32 v201, v145
	v_exp_f32_e32 v148, v164
	v_exp_f32_e32 v164, v165
	v_mfma_f32_32x32x16_bf16 v[64:79], v[218:221], v[128:131], v[64:79]
	v_exp_f32_e32 v165, v158
	v_add_f32_e32 v238, v148, v238
	v_add_f32_e32 v239, v164, v239
	ds_read_b128 v[214:217], v210 offset:49280
	ds_read_b128 v[218:221], v210 offset:61568
	s_waitcnt lgkmcnt(4)
	v_mfma_f32_32x32x16_bf16 v[80:95], v[222:225], v[124:127], v[80:95]
	v_add_f32_e32 v240, v162, v240
	v_add_f32_e32 v241, v163, v241
	v_add_f32_e32 v238, v165, v238
	v_mfma_f32_32x32x16_bf16 v[64:79], v[226:229], v[124:127], v[64:79]
	v_exp_f32_e32 v175, v159
	s_nop 0
	v_add_f32_e32 v239, v175, v239
	ds_read_b128 v[222:225], v211 offset:49280
	ds_read_b128 v[226:229], v211 offset:61568
	s_waitcnt lgkmcnt(4)
	v_mfma_f32_32x32x16_bf16 v[80:95], v[230:233], v[120:123], v[80:95]
	v_exp_f32_e32 v192, v154
	v_exp_f32_e32 v193, v155
	v_exp_f32_e32 v194, v146
	v_mfma_f32_32x32x16_bf16 v[64:79], v[234:237], v[120:123], v[64:79]
	v_exp_f32_e32 v195, v147
	v_add_f32_e32 v240, v192, v240
	v_add_f32_e32 v241, v193, v241
	v_add_f32_e32 v238, v194, v238
	ds_read_b128 v[230:233], v208 offset:49408
	ds_read_b128 v[234:237], v208 offset:61696
	s_waitcnt lgkmcnt(4)
	v_mfma_f32_32x32x16_bf16 v[80:95], v[214:217], v[116:119], v[80:95]
	v_exp_f32_e32 v196, v160
	v_exp_f32_e32 v197, v161
	v_exp_f32_e32 v198, v156
	v_mfma_f32_32x32x16_bf16 v[64:79], v[218:221], v[116:119], v[64:79]
	v_exp_f32_e32 v199, v157
	v_add_f32_e32 v239, v195, v239
	v_add_f32_e32 v240, v196, v240
	ds_read_b128 v[214:217], v209 offset:49408
	ds_read_b128 v[218:221], v209 offset:61696
	s_waitcnt lgkmcnt(4)
	v_mfma_f32_32x32x16_bf16 v[80:95], v[222:225], v[112:115], v[80:95]
	v_add_f32_e32 v241, v197, v241
	v_add_f32_e32 v238, v198, v238
	v_add_f32_e32 v239, v199, v239
	v_mfma_f32_32x32x16_bf16 v[64:79], v[226:229], v[112:115], v[64:79]
	v_add_f32_e32 v240, v200, v240
	v_add_f32_e32 v241, v201, v241
	v_add_f32_e32 v238, v238, v239
	v_add_f32_e32 v240, v240, v241
	v_add_f32_e32 v173, v238, v240
	v_mov_b32_e32 v174, v173
	ds_read_b128 v[222:225], v210 offset:49408
	ds_read_b128 v[226:229], v210 offset:61696
	s_waitcnt lgkmcnt(4)
	v_mfma_f32_32x32x16_bf16 v[80:95], v[230:233], v[108:111], v[80:95]
	v_cvt_pk_bf16_f32 v144, v186, v189
	v_cvt_pk_bf16_f32 v145, v187, v190
	v_cvt_pk_bf16_f32 v146, v188, v191
	v_mfma_f32_32x32x16_bf16 v[64:79], v[234:237], v[108:111], v[64:79]
	s_nop 1
	v_permlane32_swap_b32_e32 v173, v174
	v_cvt_pk_bf16_f32 v147, v184, v185
	v_permlane32_swap_b32_e32 v144, v146
	ds_read_b128 v[230:233], v211 offset:49408
	ds_read_b128 v[234:237], v211 offset:61696
	s_waitcnt lgkmcnt(4)
	v_mfma_f32_32x32x16_bf16 v[80:95], v[214:217], v[104:107], v[80:95]
	v_cvt_pk_bf16_f32 v154, v180, v182
	v_cvt_pk_bf16_f32 v155, v181, v183
	v_cvt_pk_bf16_f32 v156, v176, v178
	v_mfma_f32_32x32x16_bf16 v[64:79], v[218:221], v[104:107], v[64:79]
	v_cvt_pk_bf16_f32 v157, v177, v179
	v_cvt_pk_bf16_f32 v158, v148, v164
	v_cvt_pk_bf16_f32 v159, v162, v163
	s_waitcnt lgkmcnt(2)
	v_mfma_f32_32x32x16_bf16 v[80:95], v[222:225], v[100:103], v[80:95]
	v_cvt_pk_bf16_f32 v160, v165, v175
	v_cvt_pk_bf16_f32 v161, v192, v193
	v_cvt_pk_bf16_f32 v162, v194, v195
	v_mfma_f32_32x32x16_bf16 v[64:79], v[226:229], v[100:103], v[64:79]
	v_cvt_pk_bf16_f32 v163, v196, v197
	v_cvt_pk_bf16_f32 v164, v198, v199
	v_cvt_pk_bf16_f32 v165, v200, v201
	s_waitcnt lgkmcnt(0)
	v_mfma_f32_32x32x16_bf16 v[80:95], v[230:233], v[96:99], v[80:95]
	v_permlane32_swap_b32_e32 v145, v147
	v_permlane32_swap_b32_e32 v154, v156
	v_permlane32_swap_b32_e32 v155, v157
	v_mfma_f32_32x32x16_bf16 v[64:79], v[234:237], v[96:99], v[64:79]
	v_permlane32_swap_b32_e32 v158, v160
	v_permlane32_swap_b32_e32 v159, v161
	v_permlane32_swap_b32_e32 v162, v164
	v_permlane32_swap_b32_e32 v163, v165
	s_cmp_lg_u32 0, -1
	s_cselect_b32 s4, 0, 0
	s_add_i32 s44, s68, s4
	v_add_u32_e32 v148, s44, v212
	ds_read_b64_tr_b16 v[176:177], v148 offset:0
	ds_read_b64_tr_b16 v[178:179], v148 offset:0x800
	ds_read_b64_tr_b16 v[180:181], v148 offset:0x1000
	ds_read_b64_tr_b16 v[182:183], v148 offset:0x1800
	ds_read_b64_tr_b16 v[184:185], v148 offset:0x2000
	ds_read_b64_tr_b16 v[186:187], v148 offset:0x2800
	ds_read_b64_tr_b16 v[188:189], v148 offset:0x3000
	ds_read_b64_tr_b16 v[190:191], v148 offset:0x3800
	s_waitcnt lgkmcnt(0)
	s_nop 0
	v_mfma_f32_32x32x16_bf16 v[0:15], v[144:147], v[176:179], v[0:15]
	ds_read_b64_tr_b16 v[176:177], v148 offset:0x200
	ds_read_b64_tr_b16 v[178:179], v148 offset:0xa00
	v_mfma_f32_32x32x16_bf16 v[0:15], v[154:157], v[180:183], v[0:15]
	ds_read_b64_tr_b16 v[180:181], v148 offset:0x1200
	ds_read_b64_tr_b16 v[182:183], v148 offset:0x1a00
	v_mfma_f32_32x32x16_bf16 v[0:15], v[158:161], v[184:187], v[0:15]
	ds_read_b64_tr_b16 v[184:185], v148 offset:0x2200
	ds_read_b64_tr_b16 v[186:187], v148 offset:0x2a00
	v_mfma_f32_32x32x16_bf16 v[0:15], v[162:165], v[188:191], v[0:15]
	ds_read_b64_tr_b16 v[188:189], v148 offset:0x3200
	ds_read_b64_tr_b16 v[190:191], v148 offset:0x3a00
	s_waitcnt lgkmcnt(0)
	v_mfma_f32_32x32x16_bf16 v[48:63], v[144:147], v[176:179], v[48:63]
	ds_read_b64_tr_b16 v[176:177], v148 offset:0x400
	ds_read_b64_tr_b16 v[178:179], v148 offset:0xc00
	v_mfma_f32_32x32x16_bf16 v[48:63], v[154:157], v[180:183], v[48:63]
	ds_read_b64_tr_b16 v[180:181], v148 offset:0x1400
	ds_read_b64_tr_b16 v[182:183], v148 offset:0x1c00
	v_mfma_f32_32x32x16_bf16 v[48:63], v[158:161], v[184:187], v[48:63]
	ds_read_b64_tr_b16 v[184:185], v148 offset:0x2400
	ds_read_b64_tr_b16 v[186:187], v148 offset:0x2c00
	v_mfma_f32_32x32x16_bf16 v[48:63], v[162:165], v[188:191], v[48:63]
	ds_read_b64_tr_b16 v[188:189], v148 offset:0x3400
	ds_read_b64_tr_b16 v[190:191], v148 offset:0x3c00
	s_waitcnt lgkmcnt(0)
	v_mfma_f32_32x32x16_bf16 v[32:47], v[144:147], v[176:179], v[32:47]
	ds_read_b64_tr_b16 v[176:177], v148 offset:0x600
	ds_read_b64_tr_b16 v[178:179], v148 offset:0xe00
	v_mfma_f32_32x32x16_bf16 v[32:47], v[154:157], v[180:183], v[32:47]
	ds_read_b64_tr_b16 v[180:181], v148 offset:0x1600
	ds_read_b64_tr_b16 v[182:183], v148 offset:0x1e00
	v_mfma_f32_32x32x16_bf16 v[32:47], v[158:161], v[184:187], v[32:47]
	ds_read_b64_tr_b16 v[184:185], v148 offset:0x2600
	ds_read_b64_tr_b16 v[186:187], v148 offset:0x2e00
	v_mfma_f32_32x32x16_bf16 v[32:47], v[162:165], v[188:191], v[32:47]
	ds_read_b64_tr_b16 v[188:189], v148 offset:0x3600
	ds_read_b64_tr_b16 v[190:191], v148 offset:0x3e00
	s_waitcnt lgkmcnt(0)
	v_mfma_f32_32x32x16_bf16 v[16:31], v[144:147], v[176:179], v[16:31]
	v_max_f32_e32 v144, v80, v81
	v_max3_f32 v144, v144, v82, v83
	v_max3_f32 v144, v144, v84, v85
	v_max3_f32 v144, v144, v86, v87
	v_max3_f32 v144, v144, v88, v89
	v_max3_f32 v144, v144, v90, v91
	v_max3_f32 v144, v144, v92, v93
	v_mfma_f32_32x32x16_bf16 v[16:31], v[154:157], v[180:183], v[16:31]
	v_max3_f32 v144, v144, v94, v95
	v_max3_f32 v144, v144, v64, v65
	v_max3_f32 v144, v144, v66, v67
	v_max3_f32 v144, v144, v68, v69
	v_max3_f32 v144, v144, v70, v71
	v_max3_f32 v144, v144, v72, v73
	v_max3_f32 v144, v144, v74, v75
	v_max3_f32 v144, v144, v76, v77
	v_mfma_f32_32x32x16_bf16 v[16:31], v[158:161], v[184:187], v[16:31]
	v_max3_f32 v144, v144, v78, v79
	v_mov_b32_e32 v145, v144
	s_nop 1
	v_permlane32_swap_b32_e32 v144, v145
	v_max_f32_e32 v144, v144, v145
	v_sub_f32_e32 v145, v144, v172
	v_cmp_ge_f32_e32 vcc, s37, v145
	v_max_f32_e32 v144, v172, v144
	v_mfma_f32_32x32x16_bf16 v[16:31], v[162:165], v[188:191], v[16:31]
	v_sub_f32_e32 v145, v172, v144
	v_mul_f32_e32 v145, 0x3dd53b94, v145
	v_exp_f32_e32 v145, v145
	s_cmp_eq_u64 vcc, exec
	s_cselect_b64 s[4:5], -1, 0
	s_waitcnt vmcnt(0)
	v_cndmask_b32_e64 v175, v145, 1.0, s[4:5]
	v_cmp_gt_f32_e32 vcc, 1.0, v175
	s_waitcnt vmcnt(0)
	s_barrier
	s_cbranch_vccz .LBB0_454
	s_and_saveexec_b64 s[60:61], s[2:3]
	ds_write_b32 v153, v175 offset:128
	s_or_b64 exec, exec, s[60:61]
	s_waitcnt lgkmcnt(0)
	v_add_u32_e32 v145, v151, v152
	ds_read_b128 v[154:157], v145 offset:224
	ds_read_b128 v[158:161], v145 offset:192
	ds_read_b128 v[162:165], v145 offset:160
	ds_read_b128 v[176:179], v145 offset:128
	s_waitcnt lgkmcnt(3)
	v_pk_mul_f32 v[12:13], v[12:13], v[154:155]
	s_waitcnt lgkmcnt(2)
	v_pk_mul_f32 v[8:9], v[8:9], v[158:159]
	s_waitcnt lgkmcnt(1)
	v_pk_mul_f32 v[4:5], v[4:5], v[162:163]
	v_pk_mul_f32 v[14:15], v[14:15], v[156:157]
	v_pk_mul_f32 v[10:11], v[10:11], v[160:161]
	v_pk_mul_f32 v[6:7], v[6:7], v[164:165]
	s_waitcnt lgkmcnt(0)
	v_pk_mul_f32 v[2:3], v[2:3], v[178:179]
	v_pk_mul_f32 v[0:1], v[0:1], v[176:177]
	v_pk_mul_f32 v[60:61], v[60:61], v[154:155]
	v_pk_mul_f32 v[56:57], v[56:57], v[158:159]
	v_pk_mul_f32 v[52:53], v[52:53], v[162:163]
	v_pk_mul_f32 v[62:63], v[62:63], v[156:157]
	v_pk_mul_f32 v[58:59], v[58:59], v[160:161]
	v_pk_mul_f32 v[54:55], v[54:55], v[164:165]
	v_pk_mul_f32 v[50:51], v[50:51], v[178:179]
	v_pk_mul_f32 v[48:49], v[48:49], v[176:177]
	v_pk_mul_f32 v[44:45], v[44:45], v[154:155]
	v_pk_mul_f32 v[40:41], v[40:41], v[158:159]
	v_pk_mul_f32 v[36:37], v[36:37], v[162:163]
	v_pk_mul_f32 v[46:47], v[46:47], v[156:157]
	v_pk_mul_f32 v[42:43], v[42:43], v[160:161]
	v_pk_mul_f32 v[38:39], v[38:39], v[164:165]
	v_pk_mul_f32 v[34:35], v[34:35], v[178:179]
	v_pk_mul_f32 v[32:33], v[32:33], v[176:177]
	v_pk_mul_f32 v[28:29], v[28:29], v[154:155]
	v_pk_mul_f32 v[24:25], v[24:25], v[158:159]
	v_pk_mul_f32 v[20:21], v[20:21], v[162:163]
	v_pk_mul_f32 v[30:31], v[30:31], v[156:157]
	v_pk_mul_f32 v[26:27], v[26:27], v[160:161]
	v_pk_mul_f32 v[22:23], v[22:23], v[164:165]
	v_pk_mul_f32 v[18:19], v[18:19], v[178:179]
	v_pk_mul_f32 v[16:17], v[16:17], v[176:177]
.LBB0_454:
	v_cndmask_b32_e64 v154, v144, v172, s[4:5]
	v_mul_f32_e32 v176, 0xbdd53b94, v154
	v_fmamk_f32 v187, v66, 0x3dd53b94, v176
	v_fmamk_f32 v185, v64, 0x3dd53b94, v176
	v_fmamk_f32 v186, v65, 0x3dd53b94, v176
	v_fmamk_f32 v188, v67, 0x3dd53b94, v176
	s_cmp_lg_u32 0, -1
	s_cselect_b32 s4, 0, 0
	s_add_i32 s5, s4, s40
	s_add_i32 m0, s5, 0x12000
	v_fmamk_f32 v178, v69, 0x3dd53b94, v176
	s_add_u32 s98, s34, s52
	s_addc_u32 s99, s35, s53
	global_load_lds_dwordx4 v203, s[98:99]
	s_add_i32 m0, s5, 0x14000
	v_fmamk_f32 v179, v70, 0x3dd53b94, v176
	global_load_lds_dwordx4 v204, s[98:99]
	s_add_i32 m0, s5, 0x16000
	v_fmamk_f32 v189, v68, 0x3dd53b94, v176
	global_load_lds_dwordx4 v205, s[98:99]
	v_fmamk_f32 v180, v71, 0x3dd53b94, v176
	ds_read_b128 v[64:67], v208 offset:24576
	ds_read_b128 v[68:71], v208 offset:36864
	ds_read_b128 v[222:225], v209 offset:24576
	ds_read_b128 v[226:229], v209 offset:36864
	ds_read_b128 v[230:233], v210 offset:24576
	ds_read_b128 v[234:237], v210 offset:36864
	s_add_i32 s5, s41, s49
	s_mov_b32 m0, s5
	v_fmamk_f32 v80, v80, 0x3dd53b94, v176
	s_add_u32 s100, s58, s54
	s_addc_u32 s101, s59, s55
	global_load_lds_dwordx4 v206, s[100:101]
	s_add_i32 m0, s5, 0x2000
	v_exp_f32_e32 v144, v80
	global_load_lds_dwordx4 v207, s[100:101]
	v_fmamk_f32 v81, v81, 0x3dd53b94, v176
	v_fmamk_f32 v82, v82, 0x3dd53b94, v176
	v_fmamk_f32 v83, v83, 0x3dd53b94, v176
	v_fmamk_f32 v84, v84, 0x3dd53b94, v176
	v_fmamk_f32 v85, v85, 0x3dd53b94, v176
	v_fmamk_f32 v86, v86, 0x3dd53b94, v176
	v_fmamk_f32 v87, v87, 0x3dd53b94, v176
	v_fmamk_f32 v88, v88, 0x3dd53b94, v176
	v_fmamk_f32 v89, v89, 0x3dd53b94, v176
	v_fmamk_f32 v90, v90, 0x3dd53b94, v176
	v_fmamk_f32 v91, v91, 0x3dd53b94, v176
	v_fmamk_f32 v92, v92, 0x3dd53b94, v176
	v_fmamk_f32 v93, v93, 0x3dd53b94, v176
	v_fmamk_f32 v94, v94, 0x3dd53b94, v176
	v_fmamk_f32 v95, v95, 0x3dd53b94, v176
	v_fmamk_f32 v181, v72, 0x3dd53b94, v176
	v_fmamk_f32 v182, v73, 0x3dd53b94, v176
	v_fmamk_f32 v183, v74, 0x3dd53b94, v176
	v_fmamk_f32 v184, v75, 0x3dd53b94, v176
	v_fmamk_f32 v177, v76, 0x3dd53b94, v176
	v_exp_f32_e32 v172, v81
	v_exp_f32_e32 v145, v82
	v_exp_f32_e32 v165, v83
	v_exp_f32_e32 v146, v84
	v_exp_f32_e32 v164, v85
	v_exp_f32_e32 v147, v86
	v_exp_f32_e32 v163, v87
	v_exp_f32_e32 v160, v88
	v_exp_f32_e32 v162, v89
	v_exp_f32_e32 v159, v90
	v_exp_f32_e32 v161, v91
	v_exp_f32_e32 v156, v92
	v_exp_f32_e32 v158, v93
	v_exp_f32_e32 v155, v94
	v_exp_f32_e32 v157, v95
	v_fmamk_f32 v190, v77, 0x3dd53b94, v176
	v_fmamk_f32 v191, v78, 0x3dd53b94, v176
	v_fmac_f32_e32 v176, 0x3dd53b94, v79
	s_waitcnt lgkmcnt(4)
	v_mfma_f32_32x32x16_bf16 v[80:95], v[64:67], v[140:143], 0
	v_exp_f32_e32 v178, v178
	v_exp_f32_e32 v179, v179
	v_exp_f32_e32 v180, v180
	v_mfma_f32_32x32x16_bf16 v[64:79], v[68:71], v[140:143], 0
	v_exp_f32_e32 v181, v181
	v_exp_f32_e32 v182, v182
	v_exp_f32_e32 v183, v183
	ds_read_b128 v[214:217], v211 offset:24576
	ds_read_b128 v[218:221], v211 offset:36864
	s_waitcnt lgkmcnt(4)
	v_mfma_f32_32x32x16_bf16 v[80:95], v[222:225], v[136:139], v[80:95]
	v_exp_f32_e32 v184, v184
	v_exp_f32_e32 v190, v190
	v_exp_f32_e32 v191, v191
	v_mfma_f32_32x32x16_bf16 v[64:79], v[226:229], v[136:139], v[64:79]
	v_exp_f32_e32 v148, v185
	v_exp_f32_e32 v185, v186
	v_exp_f32_e32 v186, v187
	ds_read_b128 v[222:225], v208 offset:24704
	ds_read_b128 v[226:229], v208 offset:36992
	s_waitcnt lgkmcnt(4)
	v_mfma_f32_32x32x16_bf16 v[80:95], v[230:233], v[132:135], v[80:95]
	v_exp_f32_e32 v187, v188
	v_exp_f32_e32 v188, v189
	v_exp_f32_e32 v189, v177
	v_mfma_f32_32x32x16_bf16 v[64:79], v[234:237], v[132:135], v[64:79]
	v_exp_f32_e32 v194, v176
	ds_read_b128 v[230:233], v209 offset:24704
	ds_read_b128 v[234:237], v209 offset:36992
	s_waitcnt lgkmcnt(4)
	v_mfma_f32_32x32x16_bf16 v[80:95], v[214:217], v[128:131], v[80:95]
	v_add_f32_e32 v238, v144, v146
	v_mfma_f32_32x32x16_bf16 v[64:79], v[218:221], v[128:131], v[64:79]
	v_add_f32_e32 v239, v172, v164
	v_add_f32_e32 v240, v145, v147
	v_add_f32_e32 v241, v165, v163
	v_add_f32_e32 v238, v160, v238
	ds_read_b128 v[214:217], v210 offset:24704
	ds_read_b128 v[218:221], v210 offset:36992
	s_waitcnt lgkmcnt(4)
	v_mfma_f32_32x32x16_bf16 v[80:95], v[222:225], v[124:127], v[80:95]
	v_add_f32_e32 v239, v162, v239
	v_add_f32_e32 v240, v159, v240
	v_add_f32_e32 v241, v161, v241
	v_mfma_f32_32x32x16_bf16 v[64:79], v[226:229], v[124:127], v[64:79]
	v_add_f32_e32 v238, v156, v238
	v_add_f32_e32 v239, v158, v239
	v_add_f32_e32 v240, v155, v240
	ds_read_b128 v[222:225], v211 offset:24704
	ds_read_b128 v[226:229], v211 offset:36992
	s_waitcnt lgkmcnt(4)
	v_mfma_f32_32x32x16_bf16 v[80:95], v[230:233], v[120:123], v[80:95]
	v_add_f32_e32 v241, v157, v241
	v_add_f32_e32 v238, v148, v238
	v_add_f32_e32 v239, v185, v239
	v_mfma_f32_32x32x16_bf16 v[64:79], v[234:237], v[120:123], v[64:79]
	v_add_f32_e32 v240, v186, v240
	v_add_f32_e32 v241, v187, v241
	v_add_f32_e32 v238, v188, v238
	ds_read_b128 v[230:233], v208 offset:24832
	ds_read_b128 v[234:237], v208 offset:37120
	s_waitcnt lgkmcnt(4)
	v_mfma_f32_32x32x16_bf16 v[80:95], v[214:217], v[116:119], v[80:95]
	v_add_f32_e32 v239, v178, v239
	v_add_f32_e32 v240, v179, v240
	v_add_f32_e32 v241, v180, v241
	v_mfma_f32_32x32x16_bf16 v[64:79], v[218:221], v[116:119], v[64:79]
	v_add_f32_e32 v238, v181, v238
	v_add_f32_e32 v239, v182, v239
	v_add_f32_e32 v240, v183, v240
	ds_read_b128 v[214:217], v209 offset:24832
	ds_read_b128 v[218:221], v209 offset:37120
	s_waitcnt lgkmcnt(4)
	v_mfma_f32_32x32x16_bf16 v[80:95], v[222:225], v[112:115], v[80:95]
	v_add_f32_e32 v241, v184, v241
	v_add_f32_e32 v238, v189, v238
	v_add_f32_e32 v239, v190, v239
	v_mfma_f32_32x32x16_bf16 v[64:79], v[226:229], v[112:115], v[64:79]
	v_add_f32_e32 v240, v191, v240
	v_add_f32_e32 v241, v194, v241
	v_add_f32_e32 v238, v238, v239
	v_add_f32_e32 v240, v240, v241
	v_add_f32_e32 v192, v238, v240
	v_mov_b32_e32 v193, v192
	v_cvt_pk_bf16_f32 v144, v144, v172
	ds_read_b128 v[222:225], v210 offset:24832
	ds_read_b128 v[226:229], v210 offset:37120
	s_waitcnt lgkmcnt(4)
	v_mfma_f32_32x32x16_bf16 v[80:95], v[230:233], v[108:111], v[80:95]
	v_cvt_pk_bf16_f32 v145, v145, v165
	v_cvt_pk_bf16_f32 v146, v146, v164
	s_nop 1
	v_mfma_f32_32x32x16_bf16 v[64:79], v[234:237], v[108:111], v[64:79]
	v_permlane32_swap_b32_e32 v192, v193
	v_cvt_pk_bf16_f32 v147, v147, v163
	v_permlane32_swap_b32_e32 v144, v146
	ds_read_b128 v[230:233], v211 offset:24832
	ds_read_b128 v[234:237], v211 offset:37120
	s_waitcnt lgkmcnt(4)
	v_mfma_f32_32x32x16_bf16 v[80:95], v[214:217], v[104:107], v[80:95]
	v_cvt_pk_bf16_f32 v160, v160, v162
	v_cvt_pk_bf16_f32 v161, v159, v161
	v_cvt_pk_bf16_f32 v162, v156, v158
	v_mfma_f32_32x32x16_bf16 v[64:79], v[218:221], v[104:107], v[64:79]
	v_cvt_pk_bf16_f32 v163, v155, v157
	v_cvt_pk_bf16_f32 v156, v148, v185
	v_cvt_pk_bf16_f32 v157, v186, v187
	s_waitcnt lgkmcnt(2)
	v_mfma_f32_32x32x16_bf16 v[80:95], v[222:225], v[100:103], v[80:95]
	v_cvt_pk_bf16_f32 v158, v188, v178
	v_cvt_pk_bf16_f32 v159, v179, v180
	v_cvt_pk_bf16_f32 v176, v181, v182
	v_mfma_f32_32x32x16_bf16 v[64:79], v[226:229], v[100:103], v[64:79]
	v_cvt_pk_bf16_f32 v177, v183, v184
	v_cvt_pk_bf16_f32 v178, v189, v190
	v_cvt_pk_bf16_f32 v179, v191, v194
	s_waitcnt lgkmcnt(0)
	v_mfma_f32_32x32x16_bf16 v[80:95], v[230:233], v[96:99], v[80:95]
	v_permlane32_swap_b32_e32 v145, v147
	v_permlane32_swap_b32_e32 v160, v162
	v_permlane32_swap_b32_e32 v161, v163
	v_mfma_f32_32x32x16_bf16 v[64:79], v[234:237], v[96:99], v[64:79]
	v_permlane32_swap_b32_e32 v156, v158
	v_permlane32_swap_b32_e32 v157, v159
	v_permlane32_swap_b32_e32 v176, v178
	v_permlane32_swap_b32_e32 v177, v179
	s_add_i32 s4, s51, s4
	v_add_u32_e32 v148, s4, v212
	ds_read_b64_tr_b16 v[180:181], v148 offset:0
	ds_read_b64_tr_b16 v[182:183], v148 offset:0x800
	ds_read_b64_tr_b16 v[184:185], v148 offset:0x1000
	ds_read_b64_tr_b16 v[186:187], v148 offset:0x1800
	ds_read_b64_tr_b16 v[188:189], v148 offset:0x2000
	ds_read_b64_tr_b16 v[190:191], v148 offset:0x2800
	ds_read_b64_tr_b16 v[194:195], v148 offset:0x3000
	ds_read_b64_tr_b16 v[196:197], v148 offset:0x3800
	s_waitcnt lgkmcnt(0)
	s_nop 0
	v_mfma_f32_32x32x16_bf16 v[0:15], v[144:147], v[180:183], v[0:15]
	ds_read_b64_tr_b16 v[180:181], v148 offset:0x200
	ds_read_b64_tr_b16 v[182:183], v148 offset:0xa00
	v_mfma_f32_32x32x16_bf16 v[0:15], v[160:163], v[184:187], v[0:15]
	ds_read_b64_tr_b16 v[184:185], v148 offset:0x1200
	ds_read_b64_tr_b16 v[186:187], v148 offset:0x1a00
	v_mfma_f32_32x32x16_bf16 v[0:15], v[156:159], v[188:191], v[0:15]
	ds_read_b64_tr_b16 v[188:189], v148 offset:0x2200
	ds_read_b64_tr_b16 v[190:191], v148 offset:0x2a00
	v_mfma_f32_32x32x16_bf16 v[0:15], v[176:179], v[194:197], v[0:15]
	ds_read_b64_tr_b16 v[194:195], v148 offset:0x3200
	ds_read_b64_tr_b16 v[196:197], v148 offset:0x3a00
	s_waitcnt lgkmcnt(0)
	v_mfma_f32_32x32x16_bf16 v[48:63], v[144:147], v[180:183], v[48:63]
	ds_read_b64_tr_b16 v[180:181], v148 offset:0x400
	ds_read_b64_tr_b16 v[182:183], v148 offset:0xc00
	v_mfma_f32_32x32x16_bf16 v[48:63], v[160:163], v[184:187], v[48:63]
	ds_read_b64_tr_b16 v[184:185], v148 offset:0x1400
	ds_read_b64_tr_b16 v[186:187], v148 offset:0x1c00
	v_mfma_f32_32x32x16_bf16 v[48:63], v[156:159], v[188:191], v[48:63]
	ds_read_b64_tr_b16 v[188:189], v148 offset:0x2400
	ds_read_b64_tr_b16 v[190:191], v148 offset:0x2c00
	v_mfma_f32_32x32x16_bf16 v[48:63], v[176:179], v[194:197], v[48:63]
	ds_read_b64_tr_b16 v[194:195], v148 offset:0x3400
	ds_read_b64_tr_b16 v[196:197], v148 offset:0x3c00
	s_waitcnt lgkmcnt(0)
	v_mfma_f32_32x32x16_bf16 v[32:47], v[144:147], v[180:183], v[32:47]
	ds_read_b64_tr_b16 v[180:181], v148 offset:0x600
	ds_read_b64_tr_b16 v[182:183], v148 offset:0xe00
	v_mfma_f32_32x32x16_bf16 v[32:47], v[160:163], v[184:187], v[32:47]
	ds_read_b64_tr_b16 v[184:185], v148 offset:0x1600
	ds_read_b64_tr_b16 v[186:187], v148 offset:0x1e00
	v_mfma_f32_32x32x16_bf16 v[32:47], v[156:159], v[188:191], v[32:47]
	ds_read_b64_tr_b16 v[188:189], v148 offset:0x2600
	ds_read_b64_tr_b16 v[190:191], v148 offset:0x2e00
	v_mfma_f32_32x32x16_bf16 v[32:47], v[176:179], v[194:197], v[32:47]
	ds_read_b64_tr_b16 v[194:195], v148 offset:0x3600
	ds_read_b64_tr_b16 v[196:197], v148 offset:0x3e00
	s_waitcnt lgkmcnt(0)
	v_mfma_f32_32x32x16_bf16 v[16:31], v[144:147], v[180:183], v[16:31]
	v_max_f32_e32 v144, v80, v81
	v_max3_f32 v144, v144, v82, v83
	v_max3_f32 v144, v144, v84, v85
	v_max3_f32 v144, v144, v86, v87
	v_max3_f32 v144, v144, v88, v89
	v_max3_f32 v144, v144, v90, v91
	v_max3_f32 v144, v144, v92, v93
	v_mfma_f32_32x32x16_bf16 v[16:31], v[160:163], v[184:187], v[16:31]
	v_max3_f32 v144, v144, v94, v95
	v_max3_f32 v144, v144, v64, v65
	v_max3_f32 v144, v144, v66, v67
	v_max3_f32 v144, v144, v68, v69
	v_max3_f32 v144, v144, v70, v71
	v_max3_f32 v144, v144, v72, v73
	v_max3_f32 v144, v144, v74, v75
	v_max3_f32 v144, v144, v76, v77
	v_mfma_f32_32x32x16_bf16 v[16:31], v[156:159], v[188:191], v[16:31]
	v_max3_f32 v144, v144, v78, v79
	v_mov_b32_e32 v145, v144
	s_nop 1
	v_permlane32_swap_b32_e32 v144, v145
	v_max_f32_e32 v144, v144, v145
	v_sub_f32_e32 v145, v144, v154
	v_cmp_ge_f32_e32 vcc, s37, v145
	v_max_f32_e32 v144, v154, v144
	v_mfma_f32_32x32x16_bf16 v[16:31], v[176:179], v[194:197], v[16:31]
	v_sub_f32_e32 v145, v154, v144
	v_mul_f32_e32 v145, 0x3dd53b94, v145
	v_exp_f32_e32 v145, v145
	s_cmp_eq_u64 vcc, exec
	s_cselect_b64 s[4:5], -1, 0
	s_waitcnt vmcnt(0)
	v_cndmask_b32_e64 v148, v145, 1.0, s[4:5]
	v_cmp_gt_f32_e32 vcc, 1.0, v148
	s_waitcnt vmcnt(0)
	s_barrier
	s_cbranch_vccz .LBB0_458
	s_and_saveexec_b64 s[34:35], s[2:3]
	ds_write_b32 v153, v148 offset:128
	s_or_b64 exec, exec, s[34:35]
	s_waitcnt lgkmcnt(0)
	v_add_u32_e32 v145, v151, v152
	ds_read_b128 v[156:159], v145 offset:224
	ds_read_b128 v[160:163], v145 offset:192
	ds_read_b128 v[176:179], v145 offset:160
	ds_read_b128 v[180:183], v145 offset:128
	s_waitcnt lgkmcnt(3)
	v_pk_mul_f32 v[12:13], v[12:13], v[156:157]
	s_waitcnt lgkmcnt(2)
	v_pk_mul_f32 v[8:9], v[8:9], v[160:161]
	s_waitcnt lgkmcnt(1)
	v_pk_mul_f32 v[4:5], v[4:5], v[176:177]
	v_pk_mul_f32 v[14:15], v[14:15], v[158:159]
	v_pk_mul_f32 v[10:11], v[10:11], v[162:163]
	v_pk_mul_f32 v[6:7], v[6:7], v[178:179]
	s_waitcnt lgkmcnt(0)
	v_pk_mul_f32 v[2:3], v[2:3], v[182:183]
	v_pk_mul_f32 v[0:1], v[0:1], v[180:181]
	v_pk_mul_f32 v[60:61], v[60:61], v[156:157]
	v_pk_mul_f32 v[56:57], v[56:57], v[160:161]
	v_pk_mul_f32 v[52:53], v[52:53], v[176:177]
	v_pk_mul_f32 v[62:63], v[62:63], v[158:159]
	v_pk_mul_f32 v[58:59], v[58:59], v[162:163]
	v_pk_mul_f32 v[54:55], v[54:55], v[178:179]
	v_pk_mul_f32 v[50:51], v[50:51], v[182:183]
	v_pk_mul_f32 v[48:49], v[48:49], v[180:181]
	v_pk_mul_f32 v[44:45], v[44:45], v[156:157]
	v_pk_mul_f32 v[40:41], v[40:41], v[160:161]
	v_pk_mul_f32 v[36:37], v[36:37], v[176:177]
	v_pk_mul_f32 v[46:47], v[46:47], v[158:159]
	v_pk_mul_f32 v[42:43], v[42:43], v[162:163]
	v_pk_mul_f32 v[38:39], v[38:39], v[178:179]
	v_pk_mul_f32 v[34:35], v[34:35], v[182:183]
	v_pk_mul_f32 v[32:33], v[32:33], v[180:181]
	v_pk_mul_f32 v[28:29], v[28:29], v[156:157]
	v_pk_mul_f32 v[24:25], v[24:25], v[160:161]
	v_pk_mul_f32 v[20:21], v[20:21], v[176:177]
	v_pk_mul_f32 v[30:31], v[30:31], v[158:159]
	v_pk_mul_f32 v[26:27], v[26:27], v[162:163]
	v_pk_mul_f32 v[22:23], v[22:23], v[178:179]
	v_pk_mul_f32 v[18:19], v[18:19], v[182:183]
	v_pk_mul_f32 v[16:17], v[16:17], v[180:181]
.LBB0_458:
	v_cndmask_b32_e64 v172, v144, v154, s[4:5]
	v_mul_f32_e32 v144, 0xbdd53b94, v172
	v_mov_b32_e32 v145, v144
	v_pk_fma_f32 v[164:165], v[64:65], s[6:7], v[144:145] op_sel_hi:[1,0,0]
	v_pk_fma_f32 v[162:163], v[66:67], s[6:7], v[144:145] op_sel_hi:[1,0,0]
	v_pk_fma_f32 v[158:159], v[68:69], s[6:7], v[144:145] op_sel_hi:[1,0,0]
	v_pk_fma_f32 v[154:155], v[70:71], s[6:7], v[144:145] op_sel_hi:[1,0,0]
	ds_read_b128 v[64:67], v208 offset:49152
	ds_read_b128 v[68:71], v208 offset:61440
	ds_read_b128 v[222:225], v209 offset:49152
	ds_read_b128 v[226:229], v209 offset:61440
	ds_read_b128 v[230:233], v210 offset:49152
	ds_read_b128 v[234:237], v210 offset:61440
	v_fmamk_f32 v80, v80, 0x3dd53b94, v144
	v_fmamk_f32 v81, v81, 0x3dd53b94, v144
	v_fmamk_f32 v82, v82, 0x3dd53b94, v144
	v_fmamk_f32 v83, v83, 0x3dd53b94, v144
	v_fmamk_f32 v84, v84, 0x3dd53b94, v144
	v_fmamk_f32 v85, v85, 0x3dd53b94, v144
	v_fmamk_f32 v86, v86, 0x3dd53b94, v144
	v_fmamk_f32 v87, v87, 0x3dd53b94, v144
	v_fmamk_f32 v88, v88, 0x3dd53b94, v144
	v_fmamk_f32 v89, v89, 0x3dd53b94, v144
	v_fmamk_f32 v90, v90, 0x3dd53b94, v144
	v_fmamk_f32 v91, v91, 0x3dd53b94, v144
	v_fmamk_f32 v92, v92, 0x3dd53b94, v144
	v_fmamk_f32 v93, v93, 0x3dd53b94, v144
	v_fmamk_f32 v94, v94, 0x3dd53b94, v144
	v_fmac_f32_e32 v145, 0x3dd53b94, v95
	s_add_u32 s1, s1, 0x8000
	v_exp_f32_e32 v186, v80
	v_exp_f32_e32 v189, v81
	v_exp_f32_e32 v187, v82
	v_exp_f32_e32 v190, v83
	v_exp_f32_e32 v188, v84
	v_exp_f32_e32 v191, v85
	v_exp_f32_e32 v184, v86
	v_exp_f32_e32 v185, v87
	v_exp_f32_e32 v180, v88
	v_exp_f32_e32 v182, v89
	v_exp_f32_e32 v181, v90
	v_exp_f32_e32 v183, v91
	v_exp_f32_e32 v176, v92
	v_exp_f32_e32 v178, v93
	v_exp_f32_e32 v177, v94
	v_exp_f32_e32 v179, v145
	s_addc_u32 s45, s45, 0
	v_add_f32_e32 v213, v173, v174
	s_add_u32 s46, s46, 0xc000
	v_fmac_f32_e32 v213, v171, v170
	v_add_f32_e32 v170, v192, v193
	s_addc_u32 s47, s47, 0
	s_add_i32 s0, s0, 2
	v_pk_fma_f32 v[146:147], v[72:73], s[6:7], v[144:145] op_sel_hi:[1,0,0]
	v_pk_fma_f32 v[160:161], v[74:75], s[6:7], v[144:145] op_sel_hi:[1,0,0]
	v_pk_fma_f32 v[156:157], v[76:77], s[6:7], v[144:145] op_sel_hi:[1,0,0]
	v_pk_fma_f32 v[144:145], v[78:79], s[6:7], v[144:145] op_sel_hi:[1,0,0]
	s_cmp_gt_u32 s0, 64
	v_fmac_f32_e32 v170, v213, v175
	s_cbranch_scc1 .LBB0_460
	s_mov_b32 s68, s50
	s_mov_b32 s50, s51
	v_mov_b32_e32 v171, v148
	s_branch .LBB0_450
.LBB0_460:
	s_waitcnt lgkmcnt(0)
	v_mov_b32_e32 v64, v166
	v_mov_b32_e32 v67, s57
	v_and_b32_e32 v65, 31, v64
	v_lshlrev_b32_e32 v66, 3, v64
	v_lshrrev_b32_e32 v64, 1, v64
	v_and_b32_e32 v64, 16, v64
	v_and_b32_e32 v66, 0x70, v66
	v_mad_u32_u24 v65, v65, s29, v67
	v_or_b32_e32 v67, 32, v64
	v_xad_u32 v171, v64, v66, v65
	v_xad_u32 v173, v67, v66, v65
	v_or_b32_e32 v67, 64, v64
	v_or_b32_e32 v64, 0x60, v64
	v_xad_u32 v174, v67, v66, v65
	v_xad_u32 v175, v64, v66, v65
	ds_read_b128 v[64:67], v171
	ds_read_b128 v[68:71], v171 offset:12288
	s_waitcnt lgkmcnt(1)
	v_mfma_f32_32x32x16_bf16 v[80:95], v[64:67], v[140:143], 0
	s_waitcnt lgkmcnt(0)
	v_mfma_f32_32x32x16_bf16 v[64:79], v[68:71], v[140:143], 0
	ds_read_b128 v[140:143], v173
	ds_read_b128 v[192:195], v173 offset:12288
	s_waitcnt lgkmcnt(1)
	v_mfma_f32_32x32x16_bf16 v[80:95], v[140:143], v[136:139], v[80:95]
	s_waitcnt lgkmcnt(0)
	v_mfma_f32_32x32x16_bf16 v[64:79], v[192:195], v[136:139], v[64:79]
	ds_read_b128 v[136:139], v174
	ds_read_b128 v[140:143], v174 offset:12288
	s_waitcnt lgkmcnt(1)
	v_mfma_f32_32x32x16_bf16 v[80:95], v[136:139], v[132:135], v[80:95]
	s_waitcnt lgkmcnt(0)
	v_mfma_f32_32x32x16_bf16 v[64:79], v[140:143], v[132:135], v[64:79]
	ds_read_b128 v[132:135], v175
	ds_read_b128 v[136:139], v175 offset:12288
	s_waitcnt lgkmcnt(1)
	v_mfma_f32_32x32x16_bf16 v[80:95], v[132:135], v[128:131], v[80:95]
	s_waitcnt lgkmcnt(0)
	v_mfma_f32_32x32x16_bf16 v[64:79], v[136:139], v[128:131], v[64:79]
	ds_read_b128 v[128:131], v171 offset:128
	ds_read_b128 v[132:135], v171 offset:12416
	s_waitcnt lgkmcnt(1)
	v_mfma_f32_32x32x16_bf16 v[80:95], v[128:131], v[124:127], v[80:95]
	s_waitcnt lgkmcnt(0)
	v_mfma_f32_32x32x16_bf16 v[64:79], v[132:135], v[124:127], v[64:79]
	ds_read_b128 v[124:127], v173 offset:128
	ds_read_b128 v[128:131], v173 offset:12416
	s_waitcnt lgkmcnt(1)
	v_mfma_f32_32x32x16_bf16 v[80:95], v[124:127], v[120:123], v[80:95]
	s_waitcnt lgkmcnt(0)
	v_mfma_f32_32x32x16_bf16 v[64:79], v[128:131], v[120:123], v[64:79]
	ds_read_b128 v[120:123], v174 offset:128
	ds_read_b128 v[124:127], v174 offset:12416
	s_waitcnt lgkmcnt(1)
	v_mfma_f32_32x32x16_bf16 v[80:95], v[120:123], v[116:119], v[80:95]
	s_waitcnt lgkmcnt(0)
	v_mfma_f32_32x32x16_bf16 v[64:79], v[124:127], v[116:119], v[64:79]
	ds_read_b128 v[116:119], v175 offset:128
	ds_read_b128 v[120:123], v175 offset:12416
	s_waitcnt lgkmcnt(1)
	v_mfma_f32_32x32x16_bf16 v[80:95], v[116:119], v[112:115], v[80:95]
	s_waitcnt lgkmcnt(0)
	v_mfma_f32_32x32x16_bf16 v[64:79], v[120:123], v[112:115], v[64:79]
	ds_read_b128 v[112:115], v171 offset:256
	ds_read_b128 v[116:119], v171 offset:12544
	v_exp_f32_e32 v120, v144
	v_exp_f32_e32 v121, v145
	s_waitcnt lgkmcnt(1)
	v_mfma_f32_32x32x16_bf16 v[80:95], v[112:115], v[108:111], v[80:95]
	s_waitcnt lgkmcnt(0)
	v_mfma_f32_32x32x16_bf16 v[64:79], v[116:119], v[108:111], v[64:79]
	ds_read_b128 v[108:111], v173 offset:256
	ds_read_b128 v[112:115], v173 offset:12544
	v_exp_f32_e32 v116, v160
	v_exp_f32_e32 v117, v161
	v_exp_f32_e32 v118, v156
	v_exp_f32_e32 v119, v157
	s_waitcnt lgkmcnt(1)
	v_mfma_f32_32x32x16_bf16 v[80:95], v[108:111], v[104:107], v[80:95]
	s_waitcnt lgkmcnt(0)
	v_mfma_f32_32x32x16_bf16 v[64:79], v[112:115], v[104:107], v[64:79]
	ds_read_b128 v[104:107], v174 offset:256
	ds_read_b128 v[108:111], v174 offset:12544
	v_exp_f32_e32 v112, v154
	v_exp_f32_e32 v113, v155
	v_exp_f32_e32 v114, v146
	v_exp_f32_e32 v115, v147
	s_waitcnt lgkmcnt(1)
	v_mfma_f32_32x32x16_bf16 v[80:95], v[104:107], v[100:103], v[80:95]
	s_waitcnt lgkmcnt(0)
	v_mfma_f32_32x32x16_bf16 v[64:79], v[108:111], v[100:103], v[64:79]
	ds_read_b128 v[100:103], v175 offset:256
	ds_read_b128 v[104:107], v175 offset:12544
	v_exp_f32_e32 v108, v162
	v_exp_f32_e32 v109, v163
	v_exp_f32_e32 v110, v158
	v_exp_f32_e32 v111, v159
	s_waitcnt lgkmcnt(1)
	v_mfma_f32_32x32x16_bf16 v[80:95], v[100:103], v[96:99], v[80:95]
	s_waitcnt lgkmcnt(0)
	v_mfma_f32_32x32x16_bf16 v[64:79], v[104:107], v[96:99], v[64:79]
	v_add_f32_e32 v96, 0, v186
	v_add_f32_e32 v96, v189, v96
	v_add_f32_e32 v96, v187, v96
	v_add_f32_e32 v96, v190, v96
	v_add_f32_e32 v96, v188, v96
	v_add_f32_e32 v96, v191, v96
	v_add_f32_e32 v96, v184, v96
	v_add_f32_e32 v96, v185, v96
	v_add_f32_e32 v96, v180, v96
	v_add_f32_e32 v96, v182, v96
	v_add_f32_e32 v96, v181, v96
	v_add_f32_e32 v96, v183, v96
	v_exp_f32_e32 v106, v164
	v_add_f32_e32 v96, v176, v96
	v_exp_f32_e32 v107, v165
	v_add_f32_e32 v96, v178, v96
	v_add_f32_e32 v96, v177, v96
	v_add_f32_e32 v96, v179, v96
	v_add_f32_e32 v96, v106, v96
	v_add_f32_e32 v96, v107, v96
	v_add_f32_e32 v96, v108, v96
	v_add_f32_e32 v96, v109, v96
	v_add_f32_e32 v96, v110, v96
	v_add_f32_e32 v96, v111, v96
	v_add_f32_e32 v96, v112, v96
	v_add_f32_e32 v96, v113, v96
	v_add_f32_e32 v96, v114, v96
	v_add_f32_e32 v96, v115, v96
	v_add_f32_e32 v96, v116, v96
	v_add_f32_e32 v96, v117, v96
	v_add_f32_e32 v96, v118, v96
	v_add_f32_e32 v96, v119, v96
	v_add_f32_e32 v96, v120, v96
	v_add_f32_e32 v100, v121, v96
	v_mov_b32_e32 v101, v100
	v_cvt_pk_bf16_f32 v96, v186, v189
	v_cvt_pk_bf16_f32 v97, v187, v190
	v_cvt_pk_bf16_f32 v98, v188, v191
	v_cvt_pk_bf16_f32 v99, v184, v185
	s_nop 1
	v_permlane32_swap_b32_e32 v100, v101
	v_permlane32_swap_b32_e32 v96, v98
	v_permlane32_swap_b32_e32 v97, v99
	v_cvt_pk_bf16_f32 v102, v180, v182
	v_cvt_pk_bf16_f32 v103, v181, v183
	v_cvt_pk_bf16_f32 v104, v176, v178
	v_cvt_pk_bf16_f32 v105, v177, v179
	v_cvt_pk_bf16_f32 v106, v106, v107
	v_cvt_pk_bf16_f32 v107, v108, v109
	v_cvt_pk_bf16_f32 v108, v110, v111
	v_cvt_pk_bf16_f32 v109, v112, v113
	v_cvt_pk_bf16_f32 v110, v114, v115
	v_cvt_pk_bf16_f32 v111, v116, v117
	v_cvt_pk_bf16_f32 v112, v118, v119
	v_cvt_pk_bf16_f32 v113, v120, v121
	s_nop 0
	v_permlane32_swap_b32_e32 v102, v104
	v_permlane32_swap_b32_e32 v103, v105
	v_permlane32_swap_b32_e32 v106, v108
	v_permlane32_swap_b32_e32 v107, v109
	v_permlane32_swap_b32_e32 v110, v112
	v_permlane32_swap_b32_e32 v111, v113
	v_mov_b32_e32 v114, v166
	s_cmp_lg_u32 0, -1
	v_lshlrev_b32_e32 v115, 3, v114
	v_lshlrev_b32_e32 v117, 4, v114
	v_lshlrev_b32_e32 v114, 1, v114
	v_and_b32_e32 v116, 24, v115
	v_and_b32_e32 v117, 0xc0, v117
	v_and_b32_e32 v114, 32, v114
	v_or3_b32 v114, v116, v117, v114
	v_and_b32_e32 v115, 0x100, v115
	s_cselect_b32 s0, 0, 0
	v_add3_u32 v130, v115, s0, v114
	ds_read_b64_tr_b16 v[114:115], v130 offset:0
	ds_read_b64_tr_b16 v[116:117], v130 offset:0x800
	ds_read_b64_tr_b16 v[118:119], v130 offset:0x1000
	ds_read_b64_tr_b16 v[120:121], v130 offset:0x1800
	ds_read_b64_tr_b16 v[122:123], v130 offset:0x2000
	ds_read_b64_tr_b16 v[124:125], v130 offset:0x2800
	ds_read_b64_tr_b16 v[126:127], v130 offset:0x3000
	ds_read_b64_tr_b16 v[128:129], v130 offset:0x3800
	s_waitcnt lgkmcnt(0)
	s_nop 0
	v_mfma_f32_32x32x16_bf16 v[0:15], v[96:99], v[114:117], v[0:15]
	ds_read_b64_tr_b16 v[114:115], v130 offset:0x200
	ds_read_b64_tr_b16 v[116:117], v130 offset:0xa00
	v_mfma_f32_32x32x16_bf16 v[0:15], v[102:105], v[118:121], v[0:15]
	ds_read_b64_tr_b16 v[118:119], v130 offset:0x1200
	ds_read_b64_tr_b16 v[120:121], v130 offset:0x1a00
	v_mfma_f32_32x32x16_bf16 v[0:15], v[106:109], v[122:125], v[0:15]
	ds_read_b64_tr_b16 v[122:123], v130 offset:0x2200
	ds_read_b64_tr_b16 v[124:125], v130 offset:0x2a00
	v_mfma_f32_32x32x16_bf16 v[0:15], v[110:113], v[126:129], v[0:15]
	ds_read_b64_tr_b16 v[126:127], v130 offset:0x3200
	ds_read_b64_tr_b16 v[128:129], v130 offset:0x3a00
	s_waitcnt lgkmcnt(0)
	v_mfma_f32_32x32x16_bf16 v[48:63], v[96:99], v[114:117], v[48:63]
	ds_read_b64_tr_b16 v[114:115], v130 offset:0x400
	ds_read_b64_tr_b16 v[116:117], v130 offset:0xc00
	v_mfma_f32_32x32x16_bf16 v[48:63], v[102:105], v[118:121], v[48:63]
	ds_read_b64_tr_b16 v[118:119], v130 offset:0x1400
	ds_read_b64_tr_b16 v[120:121], v130 offset:0x1c00
	v_mfma_f32_32x32x16_bf16 v[48:63], v[106:109], v[122:125], v[48:63]
	ds_read_b64_tr_b16 v[122:123], v130 offset:0x2400
	ds_read_b64_tr_b16 v[124:125], v130 offset:0x2c00
	v_mfma_f32_32x32x16_bf16 v[48:63], v[110:113], v[126:129], v[48:63]
	ds_read_b64_tr_b16 v[126:127], v130 offset:0x3400
	ds_read_b64_tr_b16 v[128:129], v130 offset:0x3c00
	s_waitcnt lgkmcnt(0)
	v_mfma_f32_32x32x16_bf16 v[32:47], v[96:99], v[114:117], v[32:47]
	ds_read_b64_tr_b16 v[114:115], v130 offset:0x600
	ds_read_b64_tr_b16 v[116:117], v130 offset:0xe00
	v_mfma_f32_32x32x16_bf16 v[32:47], v[102:105], v[118:121], v[32:47]
	ds_read_b64_tr_b16 v[118:119], v130 offset:0x1600
	ds_read_b64_tr_b16 v[120:121], v130 offset:0x1e00
	v_mfma_f32_32x32x16_bf16 v[32:47], v[106:109], v[122:125], v[32:47]
	ds_read_b64_tr_b16 v[122:123], v130 offset:0x2600
	ds_read_b64_tr_b16 v[124:125], v130 offset:0x2e00
	v_mfma_f32_32x32x16_bf16 v[32:47], v[110:113], v[126:129], v[32:47]
	ds_read_b64_tr_b16 v[126:127], v130 offset:0x3600
	ds_read_b64_tr_b16 v[128:129], v130 offset:0x3e00
	s_waitcnt lgkmcnt(0)
	v_mfma_f32_32x32x16_bf16 v[16:31], v[96:99], v[114:117], v[16:31]
	v_max_f32_e32 v96, v81, v81
	v_max_f32_e32 v97, v80, v80
	v_max_f32_e32 v96, v97, v96
	v_max3_f32 v96, v96, v82, v83
	v_max3_f32 v96, v96, v84, v85
	v_max3_f32 v96, v96, v86, v87
	v_max3_f32 v96, v96, v88, v89
	v_max3_f32 v96, v96, v90, v91
	v_max3_f32 v96, v96, v92, v93
	v_mfma_f32_32x32x16_bf16 v[16:31], v[102:105], v[118:121], v[16:31]
	v_max3_f32 v96, v96, v94, v95
	v_max3_f32 v96, v96, v64, v65
	v_max3_f32 v96, v96, v66, v67
	v_max3_f32 v96, v96, v68, v69
	v_max3_f32 v96, v96, v70, v71
	v_max3_f32 v96, v96, v72, v73
	v_max3_f32 v96, v96, v74, v75
	v_max3_f32 v96, v96, v76, v77
	v_mfma_f32_32x32x16_bf16 v[16:31], v[106:109], v[122:125], v[16:31]
	v_max3_f32 v96, v96, v78, v79
	v_mov_b32_e32 v97, v96
	s_nop 1
	v_permlane32_swap_b32_e32 v96, v97
	v_max_f32_e32 v97, v97, v97
	v_max_f32_e32 v96, v96, v96
	v_max_f32_e32 v96, v96, v97
	v_sub_f32_e32 v97, v96, v172
	v_cmp_ge_f32_e32 vcc, s37, v97
	v_max_f32_e32 v97, v172, v172
	v_max_f32_e32 v97, v97, v96
	v_mfma_f32_32x32x16_bf16 v[16:31], v[110:113], v[126:129], v[16:31]
	v_sub_f32_e32 v96, v172, v97
	v_mul_f32_e32 v96, 0x3dd53b94, v96
	v_exp_f32_e32 v96, v96
	s_cmp_eq_u64 vcc, exec
	s_cselect_b64 s[4:5], -1, 0
	v_cndmask_b32_e64 v96, v96, 1.0, s[4:5]
	v_cmp_gt_f32_e32 vcc, 1.0, v96
	s_cbranch_vccz .LBB0_464
	s_and_saveexec_b64 s[34:35], s[2:3]
	ds_write_b32 v153, v96 offset:128
	s_or_b64 exec, exec, s[34:35]
	s_waitcnt lgkmcnt(0)
	v_add_u32_e32 v98, v151, v152
	ds_read_b128 v[102:105], v98 offset:224
	ds_read_b128 v[106:109], v98 offset:192
	ds_read_b128 v[110:113], v98 offset:160
	ds_read_b128 v[114:117], v98 offset:128
	s_waitcnt lgkmcnt(3)
	v_pk_mul_f32 v[12:13], v[12:13], v[102:103]
	s_waitcnt lgkmcnt(2)
	v_pk_mul_f32 v[8:9], v[8:9], v[106:107]
	s_waitcnt lgkmcnt(1)
	v_pk_mul_f32 v[4:5], v[4:5], v[110:111]
	v_pk_mul_f32 v[14:15], v[14:15], v[104:105]
	v_pk_mul_f32 v[10:11], v[10:11], v[108:109]
	v_pk_mul_f32 v[6:7], v[6:7], v[112:113]
	s_waitcnt lgkmcnt(0)
	v_pk_mul_f32 v[2:3], v[2:3], v[116:117]
	v_pk_mul_f32 v[0:1], v[0:1], v[114:115]
	v_pk_mul_f32 v[60:61], v[60:61], v[102:103]
	v_pk_mul_f32 v[56:57], v[56:57], v[106:107]
	v_pk_mul_f32 v[52:53], v[52:53], v[110:111]
	v_pk_mul_f32 v[62:63], v[62:63], v[104:105]
	v_pk_mul_f32 v[58:59], v[58:59], v[108:109]
	v_pk_mul_f32 v[54:55], v[54:55], v[112:113]
	v_pk_mul_f32 v[50:51], v[50:51], v[116:117]
	v_pk_mul_f32 v[48:49], v[48:49], v[114:115]
	v_pk_mul_f32 v[44:45], v[44:45], v[102:103]
	v_pk_mul_f32 v[40:41], v[40:41], v[106:107]
	v_pk_mul_f32 v[36:37], v[36:37], v[110:111]
	v_pk_mul_f32 v[46:47], v[46:47], v[104:105]
	v_pk_mul_f32 v[42:43], v[42:43], v[108:109]
	v_pk_mul_f32 v[38:39], v[38:39], v[112:113]
	v_pk_mul_f32 v[34:35], v[34:35], v[116:117]
	v_pk_mul_f32 v[32:33], v[32:33], v[114:115]
	v_pk_mul_f32 v[28:29], v[28:29], v[102:103]
	v_pk_mul_f32 v[24:25], v[24:25], v[106:107]
	v_pk_mul_f32 v[20:21], v[20:21], v[110:111]
	v_pk_mul_f32 v[30:31], v[30:31], v[104:105]
	v_pk_mul_f32 v[26:27], v[26:27], v[108:109]
	v_pk_mul_f32 v[22:23], v[22:23], v[112:113]
	v_pk_mul_f32 v[18:19], v[18:19], v[116:117]
	v_pk_mul_f32 v[16:17], v[16:17], v[114:115]

.LBB0_1097:
	s_lshl_b32 s0, s75, 1
	s_and_b32 s0, s0, 14
	s_ashr_i32 s35, s75, 7
	s_add_i32 s28, s0, s35
	s_ashr_i32 s29, s28, 31
	s_lshl_b32 s2, s75, 5
	s_lshl_b64 s[0:1], s[28:29], 12
	s_and_b32 s29, s2, 0xf00
	s_or_b32 s0, s0, s29
	s_mulk_i32 s1, 0x180
	s_mul_hi_u32 s2, s0, 0x180
	s_and_b32 s34, s52, 14
	s_add_i32 s2, s2, s1
	s_mulk_i32 s0, 0x180
	v_mov_b32_e32 v68, v166
	s_add_u32 s0, s14, s0
	s_addc_u32 s1, s15, s2
	v_ashrrev_i32_e32 v2, 6, v68
	v_and_b32_e32 v168, 31, v68
	v_lshlrev_b32_e32 v146, 5, v2
	s_mul_i32 s3, s28, 0x198000
	v_bfe_u32 v169, v68, 5, 1
	v_or_b32_e32 v3, v146, v168
	v_mov_b64_e32 v[0:1], s[0:1]
	s_mul_hi_i32 s2, s28, 0x198000
	s_add_u32 s4, s19, s3
	v_mad_i64_i32 v[0:1], s[0:1], v3, s54, v[0:1]
	v_lshlrev_b32_e32 v148, 4, v169
	v_mov_b32_e32 v149, v145
	s_addc_u32 s5, s30, s2
	s_mul_i32 s2, s28, 0x110000
	v_lshl_add_u64 v[0:1], v[0:1], 0, v[148:149]
	s_mul_hi_i32 s3, s28, 0x110000
	s_add_u32 s2, s31, s2
	global_load_dwordx4 v[140:143], v[0:1], off
	global_load_dwordx4 v[136:139], v[0:1], off offset:32
	global_load_dwordx4 v[132:135], v[0:1], off offset:64
	global_load_dwordx4 v[128:131], v[0:1], off offset:96
	global_load_dwordx4 v[124:127], v[0:1], off offset:128
	global_load_dwordx4 v[120:123], v[0:1], off offset:160
	global_load_dwordx4 v[116:119], v[0:1], off offset:192
	global_load_dwordx4 v[112:115], v[0:1], off offset:224
	global_load_dwordx4 v[108:111], v[0:1], off offset:256
	global_load_dwordx4 v[104:107], v[0:1], off offset:288
	global_load_dwordx4 v[100:103], v[0:1], off offset:320
	global_load_dwordx4 v[96:99], v[0:1], off offset:352
	v_readfirstlane_b32 s0, v2
	v_mov_b32_e32 v0, v166
	s_addc_u32 s3, s33, s3
	s_lshl_b32 s0, s0, 10
	s_cmp_lg_u32 0, -1
	v_mul_hi_i32 v1, v0, s57
	v_lshrrev_b32_e32 v2, 31, v1
	v_ashrrev_i32_e32 v1, 2, v1
	s_cselect_b32 s1, 0, 0
	v_add_u32_e32 v1, v1, v2
	s_add_i32 s1, s1, s0
	v_mul_lo_u32 v2, v1, s58
	v_mul_lo_u32 v3, v1, s54
	v_lshlrev_b32_e32 v1, 3, v1
	s_add_i32 s76, s1, 0xc000
	v_add_lshl_u32 v2, v2, v0, 4
	v_and_b32_e32 v1, 0x70, v1
	v_xad_u32 v1, v2, v1, v3
	s_mov_b32 m0, s76
	s_add_i32 s77, s1, 0xe000
	v_mov_b32_e32 v240, v1
	global_load_lds_dwordx4 v1, s[4:5]
	v_add_u32_e32 v1, 0x200, v0
	v_mul_hi_i32 v2, v1, s57
	v_lshrrev_b32_e32 v3, 31, v2
	v_ashrrev_i32_e32 v2, 2, v2
	v_add_u32_e32 v2, v2, v3
	v_mul_lo_u32 v3, v2, s58
	v_add_lshl_u32 v1, v3, v1, 4
	v_mul_lo_u32 v3, v2, s54
	v_lshlrev_b32_e32 v2, 3, v2
	v_and_b32_e32 v2, 0x70, v2
	v_xad_u32 v1, v1, v2, v3
	s_mov_b32 m0, s77
	s_mov_b32 s36, 0
	v_mov_b32_e32 v241, v1
	global_load_lds_dwordx4 v1, s[4:5]
	v_add_u32_e32 v1, 0x400, v0
	v_mul_hi_i32 v2, v1, s57
	v_lshrrev_b32_e32 v3, 31, v2
	v_ashrrev_i32_e32 v2, 2, v2
	v_add_u32_e32 v2, v2, v3
	v_mul_lo_u32 v3, v2, s58
	v_add_lshl_u32 v1, v3, v1, 4
	v_mul_lo_u32 v3, v2, s54
	v_lshlrev_b32_e32 v2, 3, v2
	v_and_b32_e32 v2, 0x70, v2
	v_xad_u32 v1, v1, v2, v3
	s_add_i32 m0, s1, 0x10000
	v_bfe_u32 v2, v0, 2, 2
	v_lshrrev_b32_e32 v3, 1, v0
	v_mov_b32_e32 v242, v1
	global_load_lds_dwordx4 v1, s[4:5]
	v_lshlrev_b32_e32 v1, 4, v0
	v_and_or_b32 v2, v3, 8, v2
	v_lshlrev_b32_e32 v3, 1, v0
	v_bfe_i32 v0, v0, 4, 24
	v_and_b32_e32 v4, 0xfffff0, v0
	v_lshrrev_b32_e32 v0, 1, v0
	v_and_b32_e32 v3, 0xc0, v3
	v_and_b32_e32 v0, 4, v0
	v_and_or_b32 v3, v1, 48, v3
	v_or3_b32 v0, v4, v0, v2
	v_lshl_or_b32 v0, v0, 8, v3
	s_mov_b32 m0, s1
	s_mov_b32 s37, s36
	v_mov_b32_e32 v243, v0
	global_load_lds_dwordx4 v0, s[2:3]
	v_add_u32_e32 v0, 0x2000, v1
	v_ashrrev_i32_e32 v0, 8, v0
	v_and_b32_e32 v1, 0xfffff0, v0
	v_lshrrev_b32_e32 v0, 1, v0
	v_and_b32_e32 v0, 4, v0
	v_or3_b32 v0, v1, v0, v2
	v_lshl_or_b32 v0, v0, 8, v3
	s_add_i32 m0, s1, 0x2000
	s_add_u32 s4, s4, 0x6000
	v_mov_b32_e32 v244, v0
	global_load_lds_dwordx4 v0, s[2:3]
	v_mov_b32_e32 v0, v166
	s_waitcnt vmcnt(0)
	s_waitcnt vmcnt(0) lgkmcnt(0)
	s_barrier
	s_addc_u32 s5, s5, 0
	v_mul_hi_i32 v1, v0, s57
	v_lshrrev_b32_e32 v2, 31, v1
	v_ashrrev_i32_e32 v1, 2, v1
	v_add_u32_e32 v1, v1, v2
	v_mul_lo_u32 v2, v1, s58
	v_mul_lo_u32 v3, v1, s54
	v_lshlrev_b32_e32 v1, 3, v1
	v_add_lshl_u32 v2, v2, v0, 4
	v_and_b32_e32 v1, 0x70, v1
	s_add_i32 m0, s1, 0x12000
	v_xad_u32 v1, v2, v1, v3
	global_load_lds_dwordx4 v1, s[4:5]
	v_add_u32_e32 v1, 0x200, v0
	v_mul_hi_i32 v2, v1, s57
	v_lshrrev_b32_e32 v3, 31, v2
	v_ashrrev_i32_e32 v2, 2, v2
	v_add_u32_e32 v2, v2, v3
	v_mul_lo_u32 v3, v2, s58
	v_add_lshl_u32 v1, v3, v1, 4
	v_mul_lo_u32 v3, v2, s54
	v_lshlrev_b32_e32 v2, 3, v2
	v_and_b32_e32 v2, 0x70, v2
	v_xad_u32 v1, v1, v2, v3
	s_add_i32 m0, s1, 0x14000
	s_mov_b32 s38, s36
	global_load_lds_dwordx4 v1, s[4:5]
	v_add_u32_e32 v1, 0x400, v0
	v_mul_hi_i32 v2, v1, s57
	v_lshrrev_b32_e32 v3, 31, v2
	v_ashrrev_i32_e32 v2, 2, v2
	v_add_u32_e32 v2, v2, v3
	v_mul_lo_u32 v3, v2, s58
	v_add_lshl_u32 v1, v3, v1, 4
	v_mul_lo_u32 v3, v2, s54
	v_lshlrev_b32_e32 v2, 3, v2
	v_and_b32_e32 v2, 0x70, v2
	v_xad_u32 v1, v1, v2, v3
	s_add_i32 m0, s1, 0x16000
	v_bfe_u32 v2, v0, 2, 2
	v_lshrrev_b32_e32 v3, 1, v0
	global_load_lds_dwordx4 v1, s[4:5]
	v_lshlrev_b32_e32 v1, 4, v0
	v_and_or_b32 v2, v3, 8, v2
	v_lshlrev_b32_e32 v3, 1, v0
	v_bfe_i32 v0, v0, 4, 24
	v_and_b32_e32 v4, 0xfffff0, v0
	v_lshrrev_b32_e32 v0, 1, v0
	v_and_b32_e32 v3, 0xc0, v3
	v_and_b32_e32 v0, 4, v0
	s_add_u32 s2, s2, 0x4000
	v_and_or_b32 v3, v1, 48, v3
	v_or3_b32 v0, v4, v0, v2
	s_addc_u32 s3, s3, 0
	s_add_i32 m0, s1, 0x4000
	v_lshl_or_b32 v0, v0, 8, v3
	global_load_lds_dwordx4 v0, s[2:3]
	v_add_u32_e32 v0, 0x2000, v1
	v_ashrrev_i32_e32 v0, 8, v0
	v_and_b32_e32 v1, 0xfffff0, v0
	v_lshrrev_b32_e32 v0, 1, v0
	v_and_b32_e32 v0, 4, v0
	v_or3_b32 v0, v1, v0, v2
	v_lshl_or_b32 v0, v0, 8, v3
	s_add_i32 m0, s1, 0x6000
	s_mov_b32 s39, s36
	global_load_lds_dwordx4 v0, s[2:3]
	v_mov_b32_e32 v0, v166
	s_mov_b32 s40, s36
	v_and_b32_e32 v1, 31, v0
	v_lshlrev_b32_e32 v2, 3, v0
	v_lshrrev_b32_e32 v0, 1, v0
	v_and_b32_e32 v56, 0x70, v2
	v_mad_u32_u24 v57, v1, s54, 0
	v_and_b32_e32 v58, 16, v0
	v_xad_u32 v69, v58, v56, v57
	ds_read_b128 v[0:3], v69 offset:49152
	ds_read_b128 v[4:7], v69 offset:49280
	s_waitcnt lgkmcnt(0)
	v_mfma_f32_32x32x16_bf16 v[16:31], v[0:3], v[140:143], 0
	ds_read_b128 v[0:3], v69 offset:61440
	v_or_b32_e32 v8, 32, v58
	v_xad_u32 v70, v8, v56, v57
	ds_read_b128 v[8:11], v69 offset:49408
	v_or_b32_e32 v48, 64, v58
	v_xad_u32 v71, v48, v56, v57
	v_or_b32_e32 v58, 0x60, v58
	s_waitcnt lgkmcnt(0)
	v_mfma_f32_32x32x16_bf16 v[32:47], v[0:3], v[140:143], 0
	ds_read_b128 v[0:3], v70 offset:49152
	ds_read_b128 v[12:15], v70 offset:49280
	ds_read_b128 v[48:51], v70 offset:49408
	v_xad_u32 v72, v58, v56, v57
	s_mov_b32 s41, s36
	s_mov_b32 s42, s36
	s_mov_b32 s43, s36
	s_mov_b32 s44, s36
	s_waitcnt lgkmcnt(0)
	v_mfma_f32_32x32x16_bf16 v[16:31], v[0:3], v[136:139], v[16:31]
	ds_read_b128 v[0:3], v70 offset:61440
	s_mov_b32 s45, s36
	s_mov_b32 s46, s36
	s_mov_b32 s47, s36
	s_mov_b32 s48, s36
	s_mov_b32 s49, s36
	s_mov_b32 s50, s36
	s_waitcnt lgkmcnt(0)
	v_mfma_f32_32x32x16_bf16 v[32:47], v[0:3], v[136:139], v[32:47]
	ds_read_b128 v[0:3], v71 offset:49152
	ds_read_b128 v[52:55], v71 offset:49280
	ds_read_b128 v[56:59], v71 offset:49408
	s_mov_b32 s51, s36
	s_mov_b32 s78, -1
	v_cmp_eq_u32_e64 s[2:3], 0, v169
	v_mov_b32_e32 v170, v145
	s_waitcnt lgkmcnt(0)
	v_mfma_f32_32x32x16_bf16 v[16:31], v[0:3], v[132:135], v[16:31]
	ds_read_b128 v[0:3], v71 offset:61440
	s_waitcnt lgkmcnt(0)
	v_mfma_f32_32x32x16_bf16 v[32:47], v[0:3], v[132:135], v[32:47]
	ds_read_b128 v[0:3], v72 offset:49152
	ds_read_b128 v[60:63], v72 offset:49280
	s_waitcnt lgkmcnt(0)
	v_mfma_f32_32x32x16_bf16 v[16:31], v[0:3], v[128:131], v[16:31]
	ds_read_b128 v[0:3], v72 offset:61440
	ds_read_b128 v[64:67], v72 offset:49408
	v_mfma_f32_32x32x16_bf16 v[16:31], v[4:7], v[124:127], v[16:31]
	s_waitcnt lgkmcnt(0)
	v_mfma_f32_32x32x16_bf16 v[32:47], v[0:3], v[128:131], v[32:47]
	ds_read_b128 v[0:3], v69 offset:61568
	ds_read_b128 v[4:7], v69 offset:61696
	v_mfma_f32_32x32x16_bf16 v[16:31], v[12:15], v[120:123], v[16:31]
	s_waitcnt lgkmcnt(0)
	v_mfma_f32_32x32x16_bf16 v[32:47], v[0:3], v[124:127], v[32:47]
	ds_read_b128 v[0:3], v70 offset:61568
	ds_read_b128 v[12:15], v70 offset:61696
	v_mfma_f32_32x32x16_bf16 v[16:31], v[52:55], v[116:119], v[16:31]
	s_waitcnt lgkmcnt(0)
	v_mfma_f32_32x32x16_bf16 v[32:47], v[0:3], v[120:123], v[32:47]
	ds_read_b128 v[0:3], v71 offset:61568
	ds_read_b128 v[52:55], v71 offset:61696
	v_mfma_f32_32x32x16_bf16 v[16:31], v[60:63], v[112:115], v[16:31]
	s_waitcnt lgkmcnt(0)
	v_mfma_f32_32x32x16_bf16 v[32:47], v[0:3], v[116:119], v[32:47]
	ds_read_b128 v[0:3], v72 offset:61568
	ds_read_b128 v[60:63], v72 offset:61696
	s_waitcnt vmcnt(0)
	s_waitcnt vmcnt(0) lgkmcnt(0)
	s_barrier
	v_mfma_f32_32x32x16_bf16 v[16:31], v[8:11], v[108:111], v[16:31]
	v_mfma_f32_32x32x16_bf16 v[32:47], v[0:3], v[112:115], v[32:47]
	v_and_b32_e32 v0, 0x3fffffc0, v68
	v_lshl_add_u32 v147, v0, 2, s56
	v_lshl_add_u32 v149, v168, 2, v147
	v_mfma_f32_32x32x16_bf16 v[16:31], v[48:51], v[104:107], v[16:31]
	v_mfma_f32_32x32x16_bf16 v[32:47], v[4:7], v[108:111], v[32:47]
	v_mfma_f32_32x32x16_bf16 v[16:31], v[56:59], v[100:103], v[16:31]
	v_mfma_f32_32x32x16_bf16 v[32:47], v[12:15], v[104:107], v[32:47]
	v_mov_b64_e32 v[0:1], s[36:37]
	v_mov_b64_e32 v[2:3], s[38:39]
	v_mov_b64_e32 v[4:5], s[40:41]
	v_mov_b64_e32 v[6:7], s[42:43]
	v_mov_b64_e32 v[8:9], s[44:45]
	v_mov_b64_e32 v[10:11], s[46:47]
	v_mov_b64_e32 v[12:13], s[48:49]
	v_mfma_f32_32x32x16_bf16 v[16:31], v[64:67], v[96:99], v[16:31]
	v_mov_b64_e32 v[14:15], s[50:51]
	s_movk_i32 s46, 0x4000
	s_mov_b32 s47, 0x8000
	v_mfma_f32_32x32x16_bf16 v[32:47], v[52:55], v[100:103], v[32:47]
	s_nop 7
	v_max_f32_e32 v48, v17, v17
	v_max_f32_e32 v49, v16, v16
	v_max_f32_e32 v48, v49, v48
	v_max3_f32 v48, v48, v18, v19
	v_max3_f32 v48, v48, v20, v21
	v_max3_f32 v48, v48, v22, v23
	v_max3_f32 v48, v48, v24, v25
	v_mfma_f32_32x32x16_bf16 v[32:47], v[60:63], v[96:99], v[32:47]
	v_max3_f32 v48, v48, v26, v27
	v_max3_f32 v48, v48, v28, v29
	v_max3_f32 v48, v48, v30, v31
	s_nop 8
	v_max3_f32 v48, v48, v32, v33
	v_max3_f32 v48, v48, v34, v35
	v_max3_f32 v48, v48, v36, v37
	v_max3_f32 v48, v48, v38, v39
	v_max3_f32 v48, v48, v40, v41
	v_max3_f32 v48, v48, v42, v43
	v_max3_f32 v48, v48, v44, v45
	v_max3_f32 v48, v48, v46, v47
	v_mov_b32_e32 v49, v48
	s_nop 1
	v_permlane32_swap_b32_e32 v48, v49
	v_max_f32_e32 v49, v49, v49
	v_max_f32_e32 v48, v48, v48
	v_max_f32_e32 v48, v48, v49
	v_add_f32_e32 v49, 0x7149f2ca, v48
	v_cmp_ge_f32_e32 vcc, s63, v49
	s_cmp_eq_u64 vcc, exec
	v_max_f32_e32 v48, 0xf149f2ca, v48
	s_cselect_b64 vcc, -1, 0
	v_cndmask_b32_e32 v172, v48, v167, vcc
	v_sub_f32_e32 v49, 0xf149f2ca, v48
	v_mul_f32_e32 v48, 0xbdd53b94, v172
	v_fmamk_f32 v16, v16, 0x3dd53b94, v48
	v_exp_f32_e32 v185, v16
	v_fmamk_f32 v16, v17, 0x3dd53b94, v48
	v_exp_f32_e32 v189, v16
	v_fmamk_f32 v16, v18, 0x3dd53b94, v48
	v_exp_f32_e32 v186, v16
	v_fmamk_f32 v16, v19, 0x3dd53b94, v48
	v_exp_f32_e32 v190, v16
	v_fmamk_f32 v16, v20, 0x3dd53b94, v48
	v_exp_f32_e32 v187, v16
	v_fmamk_f32 v16, v21, 0x3dd53b94, v48
	v_exp_f32_e32 v191, v16
	v_fmamk_f32 v16, v22, 0x3dd53b94, v48
	v_exp_f32_e32 v184, v16
	v_fmamk_f32 v16, v23, 0x3dd53b94, v48
	v_exp_f32_e32 v188, v16
	v_fmamk_f32 v16, v24, 0x3dd53b94, v48
	v_mul_f32_e32 v49, 0x3dd53b94, v49
	v_exp_f32_e32 v178, v16
	v_fmamk_f32 v16, v25, 0x3dd53b94, v48
	v_exp_f32_e32 v49, v49
	v_exp_f32_e32 v182, v16
	v_fmamk_f32 v16, v26, 0x3dd53b94, v48
	v_exp_f32_e32 v179, v16
	v_fmamk_f32 v16, v27, 0x3dd53b94, v48
	v_exp_f32_e32 v183, v16
	v_fmamk_f32 v16, v28, 0x3dd53b94, v48
	v_exp_f32_e32 v176, v16
	v_fmamk_f32 v16, v29, 0x3dd53b94, v48
	s_add_i32 s4, s35, s34
	v_pk_fma_f32 v[154:155], v[46:47], s[18:19], v[48:49] op_sel_hi:[1,0,0]
	v_pk_fma_f32 v[158:159], v[44:45], s[18:19], v[48:49] op_sel_hi:[1,0,0]
	v_pk_fma_f32 v[164:165], v[42:43], s[18:19], v[48:49] op_sel_hi:[1,0,0]
	v_pk_fma_f32 v[150:151], v[40:41], s[18:19], v[48:49] op_sel_hi:[1,0,0]
	v_pk_fma_f32 v[152:153], v[38:39], s[18:19], v[48:49] op_sel_hi:[1,0,0]
	v_pk_fma_f32 v[156:157], v[36:37], s[18:19], v[48:49] op_sel_hi:[1,0,0]
	v_pk_fma_f32 v[160:161], v[34:35], s[18:19], v[48:49] op_sel_hi:[1,0,0]
	v_pk_fma_f32 v[162:163], v[32:33], s[18:19], v[48:49] op_sel_hi:[1,0,0]
	v_exp_f32_e32 v180, v16
	v_fmamk_f32 v16, v30, 0x3dd53b94, v48
	v_fmac_f32_e32 v48, 0x3dd53b94, v31
	s_mul_i32 s34, s4, 0x110000
	v_exp_f32_e32 v177, v16
	v_exp_f32_e32 v181, v48
	s_mul_hi_i32 s5, s4, 0x110000
	s_add_u32 s41, s86, s34
	s_addc_u32 s42, s87, s5
	s_mul_hi_i32 s5, s4, 0x198000
	s_mul_i32 s4, s4, 0x198000
	v_cndmask_b32_e64 v171, v49, 1.0, vcc
	s_add_u32 s43, s86, s4
	v_mov_b64_e32 v[62:63], v[14:15]
	v_mov_b64_e32 v[46:47], v[14:15]
	v_mov_b64_e32 v[30:31], v[14:15]
	s_addc_u32 s44, s87, s5
	s_add_i32 s45, s76, 0x4000
	v_mov_b64_e32 v[60:61], v[12:13]
	v_mov_b64_e32 v[58:59], v[10:11]
	v_mov_b64_e32 v[56:57], v[8:9]
	v_mov_b64_e32 v[54:55], v[6:7]
	v_mov_b64_e32 v[52:53], v[4:5]
	v_mov_b64_e32 v[50:51], v[2:3]
	v_mov_b64_e32 v[48:49], v[0:1]
	v_mov_b64_e32 v[44:45], v[12:13]
	v_mov_b64_e32 v[42:43], v[10:11]
	v_mov_b64_e32 v[40:41], v[8:9]
	v_mov_b64_e32 v[38:39], v[6:7]
	v_mov_b64_e32 v[36:37], v[4:5]
	v_mov_b64_e32 v[34:35], v[2:3]
	v_mov_b64_e32 v[32:33], v[0:1]
	v_mov_b64_e32 v[28:29], v[12:13]
	v_mov_b64_e32 v[26:27], v[10:11]
	v_mov_b64_e32 v[24:25], v[8:9]
	v_mov_b64_e32 v[22:23], v[6:7]
	v_mov_b64_e32 v[20:21], v[4:5]
	v_mov_b64_e32 v[18:19], v[2:3]
	v_mov_b64_e32 v[16:17], v[0:1]
	v_and_b32_e32 v65, 31, v166
	v_lshlrev_b32_e32 v66, 3, v166
	v_and_b32_e32 v66, 0x70, v66
	v_lshrrev_b32_e32 v64, 1, v166
	v_and_b32_e32 v64, 16, v64
	s_movk_i32 s98, 0x6000
	v_mov_b32_e32 v67, s98
	v_mad_u32_u24 v65, v65, s54, v67
	v_xad_u32 v246, v64, v66, v65
	v_or_b32_e32 v67, 32, v64
	v_xad_u32 v247, v67, v66, v65
	v_or_b32_e32 v67, 64, v64
	v_xad_u32 v248, v67, v66, v65
	v_or_b32_e32 v67, 0x60, v64
	v_xad_u32 v249, v67, v66, v65
	v_lshlrev_b32_e32 v64, 3, v166
	v_lshlrev_b32_e32 v65, 4, v166
	v_lshlrev_b32_e32 v66, 1, v166
	v_and_b32_e32 v67, 24, v64
	v_and_b32_e32 v65, 0xc0, v65
	v_and_b32_e32 v66, 32, v66
	v_or3_b32 v66, v67, v65, v66
	v_and_b32_e32 v64, 0x100, v64
	v_add_u32_e32 v250, v64, v66
	ds_read_b128 v[64:67], v246 offset:49152
	ds_read_b128 v[68:71], v246 offset:61440
	ds_read_b128 v[232:235], v247 offset:49152
	ds_read_b128 v[236:239], v247 offset:61440
	ds_read_b128 v[200:203], v248 offset:49152
	ds_read_b128 v[204:207], v248 offset:61440
.LBB0_1098:
	s_add_u32 s34, s43, s16
	s_addc_u32 s35, s44, s17
	s_mov_b32 m0, s76
	s_add_u32 s98, s34, s20
	s_addc_u32 s99, s35, s21
	global_load_lds_dwordx4 v240, s[98:99]
	s_mov_b32 m0, s77
	s_nop 0
	global_load_lds_dwordx4 v241, s[98:99]
	s_mov_b32 m0, s45
	s_nop 0
	global_load_lds_dwordx4 v242, s[98:99]
	s_add_i32 s4, s1, s47
	s_add_u32 s38, s41, s16
	s_addc_u32 s39, s42, s17
	s_mov_b32 m0, s4
	s_mov_b32 s48, s46
	s_add_u32 s100, s38, s22
	s_addc_u32 s101, s39, s23
	global_load_lds_dwordx4 v243, s[100:101]
	s_add_i32 m0, s4, 0x2000
	s_mov_b32 s46, s36
	global_load_lds_dwordx4 v244, s[100:101]
	s_add_i32 s49, 0, 0x12000
	s_waitcnt lgkmcnt(4)
	v_mfma_f32_32x32x16_bf16 v[80:95], v[64:67], v[140:143], 0
	v_exp_f32_e32 v160, v160
	v_exp_f32_e32 v161, v161
	v_exp_f32_e32 v164, v164
	v_mfma_f32_32x32x16_bf16 v[64:79], v[68:71], v[140:143], 0
	v_exp_f32_e32 v165, v165
	v_exp_f32_e32 v175, v157
	v_exp_f32_e32 v144, v162
	ds_read_b128 v[216:219], v249 offset:49152
	ds_read_b128 v[220:223], v249 offset:61440
	s_waitcnt lgkmcnt(4)
	v_mfma_f32_32x32x16_bf16 v[80:95], v[232:235], v[136:139], v[80:95]
	v_exp_f32_e32 v162, v163
	v_exp_f32_e32 v163, v156
	v_exp_f32_e32 v214, v150
	v_mfma_f32_32x32x16_bf16 v[64:79], v[236:239], v[136:139], v[64:79]
	ds_read_b128 v[232:235], v246 offset:49280
	ds_read_b128 v[236:239], v246 offset:61568
	s_waitcnt lgkmcnt(4)
	v_mfma_f32_32x32x16_bf16 v[80:95], v[200:203], v[132:135], v[80:95]
	v_add_f32_e32 v224, v185, v187
	v_add_f32_e32 v225, v189, v191
	v_mfma_f32_32x32x16_bf16 v[64:79], v[204:207], v[132:135], v[64:79]
	v_add_f32_e32 v226, v186, v184
	v_add_f32_e32 v227, v190, v188
	v_add_f32_e32 v224, v178, v224
	ds_read_b128 v[200:203], v247 offset:49280
	ds_read_b128 v[204:207], v247 offset:61568
	s_waitcnt lgkmcnt(4)
	v_mfma_f32_32x32x16_bf16 v[80:95], v[216:219], v[128:131], v[80:95]
	v_add_f32_e32 v225, v182, v225
	v_add_f32_e32 v226, v179, v226
	v_add_f32_e32 v227, v183, v227
	v_mfma_f32_32x32x16_bf16 v[64:79], v[220:223], v[128:131], v[64:79]
	v_add_f32_e32 v224, v176, v224
	v_add_f32_e32 v225, v180, v225
	v_add_f32_e32 v226, v177, v226
	v_add_f32_e32 v227, v181, v227
	ds_read_b128 v[216:219], v248 offset:49280
	ds_read_b128 v[220:223], v248 offset:61568
	s_waitcnt lgkmcnt(4)
	v_mfma_f32_32x32x16_bf16 v[80:95], v[232:235], v[124:127], v[80:95]
	v_add_f32_e32 v224, v144, v224
	v_add_f32_e32 v225, v162, v225
	v_exp_f32_e32 v212, v152
	v_mfma_f32_32x32x16_bf16 v[64:79], v[236:239], v[124:127], v[64:79]
	v_add_f32_e32 v226, v160, v226
	v_exp_f32_e32 v213, v153
	v_add_f32_e32 v227, v161, v227
	ds_read_b128 v[232:235], v249 offset:49280
	ds_read_b128 v[236:239], v249 offset:61568
	s_waitcnt lgkmcnt(4)
	v_mfma_f32_32x32x16_bf16 v[80:95], v[200:203], v[120:123], v[80:95]
	v_add_f32_e32 v224, v163, v224
	v_exp_f32_e32 v215, v151
	v_add_f32_e32 v225, v175, v225
	v_mfma_f32_32x32x16_bf16 v[64:79], v[204:207], v[120:123], v[64:79]
	v_add_f32_e32 v226, v212, v226
	v_add_f32_e32 v227, v213, v227
	v_exp_f32_e32 v228, v158
	ds_read_b128 v[200:203], v246 offset:49408
	ds_read_b128 v[204:207], v246 offset:61696
	s_waitcnt lgkmcnt(4)
	v_mfma_f32_32x32x16_bf16 v[80:95], v[216:219], v[116:119], v[80:95]
	v_add_f32_e32 v224, v214, v224
	v_exp_f32_e32 v229, v159
	v_add_f32_e32 v225, v215, v225
	v_mfma_f32_32x32x16_bf16 v[64:79], v[220:223], v[116:119], v[64:79]
	v_exp_f32_e32 v230, v154
	v_add_f32_e32 v226, v164, v226
	v_exp_f32_e32 v231, v155
	ds_read_b128 v[216:219], v247 offset:49408
	ds_read_b128 v[220:223], v247 offset:61696
	s_waitcnt lgkmcnt(4)
	v_mfma_f32_32x32x16_bf16 v[80:95], v[232:235], v[112:115], v[80:95]
	v_add_f32_e32 v227, v165, v227
	v_add_f32_e32 v224, v228, v224
	v_add_f32_e32 v225, v229, v225
	v_mfma_f32_32x32x16_bf16 v[64:79], v[236:239], v[112:115], v[64:79]
	v_add_f32_e32 v226, v230, v226
	v_add_f32_e32 v227, v231, v227
	v_add_f32_e32 v224, v224, v225
	v_add_f32_e32 v226, v226, v227
	v_add_f32_e32 v173, v224, v226
	v_mov_b32_e32 v174, v173
	s_nop 1
	ds_read_b128 v[232:235], v248 offset:49408
	ds_read_b128 v[236:239], v248 offset:61696
	s_waitcnt lgkmcnt(4)
	v_mfma_f32_32x32x16_bf16 v[80:95], v[200:203], v[108:111], v[80:95]
	v_permlane32_swap_b32_e32 v173, v174
	v_cvt_pk_bf16_f32 v150, v185, v189
	v_cvt_pk_bf16_f32 v151, v186, v190
	v_mfma_f32_32x32x16_bf16 v[64:79], v[204:207], v[108:111], v[64:79]
	v_cvt_pk_bf16_f32 v152, v187, v191
	v_cvt_pk_bf16_f32 v153, v184, v188
	v_cvt_pk_bf16_f32 v154, v178, v182
	ds_read_b128 v[200:203], v249 offset:49408
	ds_read_b128 v[204:207], v249 offset:61696
	s_waitcnt lgkmcnt(4)
	v_mfma_f32_32x32x16_bf16 v[80:95], v[216:219], v[104:107], v[80:95]
	v_cvt_pk_bf16_f32 v155, v179, v183
	v_cvt_pk_bf16_f32 v156, v176, v180
	v_cvt_pk_bf16_f32 v157, v177, v181
	v_mfma_f32_32x32x16_bf16 v[64:79], v[220:223], v[104:107], v[64:79]
	v_cvt_pk_bf16_f32 v158, v144, v162
	v_cvt_pk_bf16_f32 v159, v160, v161
	v_cvt_pk_bf16_f32 v160, v163, v175
	s_waitcnt lgkmcnt(2)
	v_mfma_f32_32x32x16_bf16 v[80:95], v[232:235], v[100:103], v[80:95]
	v_cvt_pk_bf16_f32 v161, v212, v213
	v_cvt_pk_bf16_f32 v162, v214, v215
	v_cvt_pk_bf16_f32 v163, v164, v165
	v_mfma_f32_32x32x16_bf16 v[64:79], v[236:239], v[100:103], v[64:79]
	v_cvt_pk_bf16_f32 v164, v228, v229
	v_cvt_pk_bf16_f32 v165, v230, v231
	v_permlane32_swap_b32_e32 v150, v152
	s_waitcnt lgkmcnt(0)
	v_mfma_f32_32x32x16_bf16 v[80:95], v[200:203], v[96:99], v[80:95]
	v_permlane32_swap_b32_e32 v151, v153
	v_permlane32_swap_b32_e32 v154, v156
	v_permlane32_swap_b32_e32 v155, v157
	v_mfma_f32_32x32x16_bf16 v[64:79], v[204:207], v[96:99], v[64:79]
	v_permlane32_swap_b32_e32 v158, v160
	v_permlane32_swap_b32_e32 v159, v161
	v_permlane32_swap_b32_e32 v162, v164
	v_permlane32_swap_b32_e32 v163, v165
	s_cmp_lg_u32 0, -1
	s_cselect_b32 s4, 0, 0
	s_add_i32 s40, s36, s4
	v_add_u32_e32 v144, s40, v250
	ds_read_b64_tr_b16 v[176:177], v144 offset:0
	ds_read_b64_tr_b16 v[178:179], v144 offset:0x800
	ds_read_b64_tr_b16 v[180:181], v144 offset:0x1000
	ds_read_b64_tr_b16 v[182:183], v144 offset:0x1800
	ds_read_b64_tr_b16 v[184:185], v144 offset:0x2000
	ds_read_b64_tr_b16 v[186:187], v144 offset:0x2800
	ds_read_b64_tr_b16 v[188:189], v144 offset:0x3000
	ds_read_b64_tr_b16 v[190:191], v144 offset:0x3800
	s_waitcnt lgkmcnt(0)
	s_nop 0
	v_mfma_f32_32x32x16_bf16 v[0:15], v[150:153], v[176:179], v[0:15]
	ds_read_b64_tr_b16 v[176:177], v144 offset:0x200
	ds_read_b64_tr_b16 v[178:179], v144 offset:0xa00
	v_mfma_f32_32x32x16_bf16 v[0:15], v[154:157], v[180:183], v[0:15]
	ds_read_b64_tr_b16 v[180:181], v144 offset:0x1200
	ds_read_b64_tr_b16 v[182:183], v144 offset:0x1a00
	v_mfma_f32_32x32x16_bf16 v[0:15], v[158:161], v[184:187], v[0:15]
	ds_read_b64_tr_b16 v[184:185], v144 offset:0x2200
	ds_read_b64_tr_b16 v[186:187], v144 offset:0x2a00
	ds_read_b64_tr_b16 v[192:193], v144 offset:0x3200
	ds_read_b64_tr_b16 v[194:195], v144 offset:0x3a00
	s_waitcnt lgkmcnt(0)
	v_mfma_f32_32x32x16_bf16 v[0:15], v[162:165], v[188:191], v[0:15]
	v_mfma_f32_32x32x16_bf16 v[48:63], v[150:153], v[176:179], v[48:63]
	ds_read_b64_tr_b16 v[176:177], v144 offset:0x400
	ds_read_b64_tr_b16 v[178:179], v144 offset:0xc00
	v_mfma_f32_32x32x16_bf16 v[48:63], v[154:157], v[180:183], v[48:63]
	ds_read_b64_tr_b16 v[180:181], v144 offset:0x1400
	ds_read_b64_tr_b16 v[182:183], v144 offset:0x1c00
	v_mfma_f32_32x32x16_bf16 v[48:63], v[158:161], v[184:187], v[48:63]
	ds_read_b64_tr_b16 v[184:185], v144 offset:0x2400
	ds_read_b64_tr_b16 v[186:187], v144 offset:0x2c00
	ds_read_b64_tr_b16 v[188:189], v144 offset:0x3400
	ds_read_b64_tr_b16 v[190:191], v144 offset:0x3c00
	s_waitcnt lgkmcnt(0)
	v_mfma_f32_32x32x16_bf16 v[48:63], v[162:165], v[192:195], v[48:63]
	v_mfma_f32_32x32x16_bf16 v[32:47], v[150:153], v[176:179], v[32:47]
	ds_read_b64_tr_b16 v[176:177], v144 offset:0x600
	ds_read_b64_tr_b16 v[178:179], v144 offset:0xe00
	v_mfma_f32_32x32x16_bf16 v[32:47], v[154:157], v[180:183], v[32:47]
	ds_read_b64_tr_b16 v[180:181], v144 offset:0x1600
	ds_read_b64_tr_b16 v[182:183], v144 offset:0x1e00
	v_mfma_f32_32x32x16_bf16 v[32:47], v[158:161], v[184:187], v[32:47]
	ds_read_b64_tr_b16 v[184:185], v144 offset:0x2600
	ds_read_b64_tr_b16 v[186:187], v144 offset:0x2e00
	ds_read_b64_tr_b16 v[192:193], v144 offset:0x3600
	ds_read_b64_tr_b16 v[194:195], v144 offset:0x3e00
	s_waitcnt lgkmcnt(0)
	v_mfma_f32_32x32x16_bf16 v[32:47], v[162:165], v[188:191], v[32:47]
	v_mfma_f32_32x32x16_bf16 v[16:31], v[150:153], v[176:179], v[16:31]
	v_max_f32_e32 v144, v80, v81
	v_max3_f32 v144, v144, v82, v83
	v_max3_f32 v144, v144, v84, v85
	v_max3_f32 v144, v144, v86, v87
	v_max3_f32 v144, v144, v88, v89
	v_max3_f32 v144, v144, v90, v91
	v_mfma_f32_32x32x16_bf16 v[16:31], v[154:157], v[180:183], v[16:31]
	v_max3_f32 v144, v144, v92, v93
	v_max3_f32 v144, v144, v94, v95
	v_max3_f32 v144, v144, v64, v65
	v_max3_f32 v144, v144, v66, v67
	v_max3_f32 v144, v144, v68, v69
	v_max3_f32 v144, v144, v70, v71
	v_max3_f32 v144, v144, v72, v73
	v_max3_f32 v144, v144, v74, v75
	v_mfma_f32_32x32x16_bf16 v[16:31], v[158:161], v[184:187], v[16:31]
	v_max3_f32 v144, v144, v76, v77
	v_max3_f32 v144, v144, v78, v79
	v_mov_b32_e32 v150, v144
	s_nop 1
	v_permlane32_swap_b32_e32 v144, v150
	v_max_f32_e32 v144, v144, v150
	v_sub_f32_e32 v150, v144, v172
	v_max_f32_e32 v144, v172, v144
	v_mfma_f32_32x32x16_bf16 v[16:31], v[162:165], v[192:195], v[16:31]
	v_sub_f32_e32 v151, v172, v144
	v_mul_f32_e32 v151, 0x3dd53b94, v151
	v_exp_f32_e32 v151, v151
	v_cmp_ge_f32_e32 vcc, s63, v150
	s_cmp_eq_u64 vcc, exec
	s_cselect_b64 s[4:5], -1, 0
	s_waitcnt vmcnt(0)
	v_cndmask_b32_e64 v175, v151, 1.0, s[4:5]
	v_cmp_gt_f32_e32 vcc, 1.0, v175
	s_waitcnt vmcnt(0)
	s_barrier
	s_cbranch_vccz .LBB0_1102
	s_and_saveexec_b64 s[36:37], s[2:3]
	ds_write_b32 v149, v175 offset:128
	s_or_b64 exec, exec, s[36:37]
	s_waitcnt lgkmcnt(0)
	v_add_u32_e32 v162, v147, v148
	ds_read_b128 v[150:153], v162 offset:224
	ds_read_b128 v[154:157], v162 offset:192
	ds_read_b128 v[158:161], v162 offset:160
	ds_read_b128 v[162:165], v162 offset:128
	s_waitcnt lgkmcnt(3)
	v_pk_mul_f32 v[12:13], v[12:13], v[150:151]
	s_waitcnt lgkmcnt(2)
	v_pk_mul_f32 v[8:9], v[8:9], v[154:155]
	s_waitcnt lgkmcnt(1)
	v_pk_mul_f32 v[4:5], v[4:5], v[158:159]
	v_pk_mul_f32 v[14:15], v[14:15], v[152:153]
	v_pk_mul_f32 v[10:11], v[10:11], v[156:157]
	v_pk_mul_f32 v[6:7], v[6:7], v[160:161]
	s_waitcnt lgkmcnt(0)
	v_pk_mul_f32 v[2:3], v[2:3], v[164:165]
	v_pk_mul_f32 v[0:1], v[0:1], v[162:163]
	v_pk_mul_f32 v[60:61], v[60:61], v[150:151]
	v_pk_mul_f32 v[56:57], v[56:57], v[154:155]
	v_pk_mul_f32 v[52:53], v[52:53], v[158:159]
	v_pk_mul_f32 v[62:63], v[62:63], v[152:153]
	v_pk_mul_f32 v[58:59], v[58:59], v[156:157]
	v_pk_mul_f32 v[54:55], v[54:55], v[160:161]
	v_pk_mul_f32 v[50:51], v[50:51], v[164:165]
	v_pk_mul_f32 v[48:49], v[48:49], v[162:163]
	v_pk_mul_f32 v[44:45], v[44:45], v[150:151]
	v_pk_mul_f32 v[40:41], v[40:41], v[154:155]
	v_pk_mul_f32 v[36:37], v[36:37], v[158:159]
	v_pk_mul_f32 v[46:47], v[46:47], v[152:153]
	v_pk_mul_f32 v[42:43], v[42:43], v[156:157]
	v_pk_mul_f32 v[38:39], v[38:39], v[160:161]
	v_pk_mul_f32 v[34:35], v[34:35], v[164:165]
	v_pk_mul_f32 v[32:33], v[32:33], v[162:163]
	v_pk_mul_f32 v[28:29], v[28:29], v[150:151]
	v_pk_mul_f32 v[24:25], v[24:25], v[154:155]
	v_pk_mul_f32 v[20:21], v[20:21], v[158:159]
	v_pk_mul_f32 v[30:31], v[30:31], v[152:153]
	v_pk_mul_f32 v[26:27], v[26:27], v[156:157]
	v_pk_mul_f32 v[22:23], v[22:23], v[160:161]
	v_pk_mul_f32 v[18:19], v[18:19], v[164:165]
	v_pk_mul_f32 v[16:17], v[16:17], v[162:163]
.LBB0_1102:
	v_cndmask_b32_e64 v150, v144, v172, s[4:5]
	v_mul_f32_e32 v176, 0xbdd53b94, v150
	v_fmamk_f32 v187, v66, 0x3dd53b94, v176
	v_fmamk_f32 v185, v64, 0x3dd53b94, v176
	v_fmamk_f32 v186, v65, 0x3dd53b94, v176
	v_fmamk_f32 v188, v67, 0x3dd53b94, v176
	s_cmp_lg_u32 0, -1
	s_cselect_b32 s4, 0, 0
	s_add_i32 s5, s4, s0
	s_add_i32 m0, s5, 0x12000
	v_fmamk_f32 v178, v69, 0x3dd53b94, v176
	s_add_u32 s98, s34, s24
	s_addc_u32 s99, s35, s25
	global_load_lds_dwordx4 v240, s[98:99]
	s_add_i32 m0, s5, 0x14000
	v_fmamk_f32 v179, v70, 0x3dd53b94, v176
	global_load_lds_dwordx4 v241, s[98:99]
	s_add_i32 m0, s5, 0x16000
	v_fmamk_f32 v189, v68, 0x3dd53b94, v176
	global_load_lds_dwordx4 v242, s[98:99]
	v_fmamk_f32 v180, v71, 0x3dd53b94, v176
	ds_read_b128 v[64:67], v246 offset:24576
	ds_read_b128 v[68:71], v246 offset:36864
	ds_read_b128 v[232:235], v247 offset:24576
	ds_read_b128 v[236:239], v247 offset:36864
	ds_read_b128 v[200:203], v248 offset:24576
	ds_read_b128 v[204:207], v248 offset:36864
	s_add_i32 s5, s1, s46
	s_mov_b32 m0, s5
	v_fmamk_f32 v94, v94, 0x3dd53b94, v176
	s_add_u32 s100, s38, s26
	s_addc_u32 s101, s39, s27
	global_load_lds_dwordx4 v243, s[100:101]
	s_add_i32 m0, s5, 0x2000
	v_exp_f32_e32 v151, v94
	global_load_lds_dwordx4 v244, s[100:101]
	v_fmamk_f32 v80, v80, 0x3dd53b94, v176
	v_fmamk_f32 v81, v81, 0x3dd53b94, v176
	v_fmamk_f32 v82, v82, 0x3dd53b94, v176
	v_fmamk_f32 v83, v83, 0x3dd53b94, v176
	v_fmamk_f32 v84, v84, 0x3dd53b94, v176
	v_fmamk_f32 v85, v85, 0x3dd53b94, v176
	v_fmamk_f32 v86, v86, 0x3dd53b94, v176
	v_fmamk_f32 v87, v87, 0x3dd53b94, v176
	v_fmamk_f32 v88, v88, 0x3dd53b94, v176
	v_fmamk_f32 v89, v89, 0x3dd53b94, v176
	v_fmamk_f32 v90, v90, 0x3dd53b94, v176
	v_fmamk_f32 v91, v91, 0x3dd53b94, v176
	v_fmamk_f32 v92, v92, 0x3dd53b94, v176
	v_fmamk_f32 v93, v93, 0x3dd53b94, v176
	v_fmamk_f32 v95, v95, 0x3dd53b94, v176
	v_fmamk_f32 v181, v72, 0x3dd53b94, v176
	v_fmamk_f32 v182, v73, 0x3dd53b94, v176
	v_fmamk_f32 v183, v74, 0x3dd53b94, v176
	v_fmamk_f32 v184, v75, 0x3dd53b94, v176
	v_fmamk_f32 v177, v76, 0x3dd53b94, v176
	v_exp_f32_e32 v164, v80
	v_exp_f32_e32 v172, v81
	v_exp_f32_e32 v162, v82
	v_exp_f32_e32 v165, v83
	v_exp_f32_e32 v161, v84
	v_exp_f32_e32 v163, v85
	v_exp_f32_e32 v159, v86
	v_exp_f32_e32 v160, v87
	v_exp_f32_e32 v156, v88
	v_exp_f32_e32 v158, v89
	v_exp_f32_e32 v155, v90
	v_exp_f32_e32 v157, v91
	v_exp_f32_e32 v152, v92
	v_exp_f32_e32 v154, v93
	v_exp_f32_e32 v153, v95
	v_fmamk_f32 v190, v77, 0x3dd53b94, v176
	v_fmamk_f32 v191, v78, 0x3dd53b94, v176
	v_fmac_f32_e32 v176, 0x3dd53b94, v79
	s_waitcnt lgkmcnt(4)
	v_mfma_f32_32x32x16_bf16 v[80:95], v[64:67], v[140:143], 0
	v_exp_f32_e32 v180, v180
	v_exp_f32_e32 v181, v181
	v_exp_f32_e32 v182, v182
	v_mfma_f32_32x32x16_bf16 v[64:79], v[68:71], v[140:143], 0
	v_exp_f32_e32 v183, v183
	v_exp_f32_e32 v184, v184
	v_exp_f32_e32 v190, v190
	ds_read_b128 v[216:219], v249 offset:24576
	ds_read_b128 v[220:223], v249 offset:36864
	s_waitcnt lgkmcnt(4)
	v_mfma_f32_32x32x16_bf16 v[80:95], v[232:235], v[136:139], v[80:95]
	v_exp_f32_e32 v191, v191
	v_exp_f32_e32 v144, v185
	v_exp_f32_e32 v185, v186
	v_mfma_f32_32x32x16_bf16 v[64:79], v[236:239], v[136:139], v[64:79]
	v_exp_f32_e32 v186, v187
	v_exp_f32_e32 v187, v188
	v_exp_f32_e32 v188, v189
	ds_read_b128 v[232:235], v246 offset:24704
	ds_read_b128 v[236:239], v246 offset:36992
	s_waitcnt lgkmcnt(4)
	v_mfma_f32_32x32x16_bf16 v[80:95], v[200:203], v[132:135], v[80:95]
	v_exp_f32_e32 v189, v178
	v_exp_f32_e32 v214, v176
	v_mfma_f32_32x32x16_bf16 v[64:79], v[204:207], v[132:135], v[64:79]
	ds_read_b128 v[200:203], v247 offset:24704
	ds_read_b128 v[204:207], v247 offset:36992
	s_waitcnt lgkmcnt(4)
	v_mfma_f32_32x32x16_bf16 v[80:95], v[216:219], v[128:131], v[80:95]
	v_add_f32_e32 v224, v164, v161
	v_add_f32_e32 v225, v172, v163
	v_add_f32_e32 v226, v162, v159
	v_mfma_f32_32x32x16_bf16 v[64:79], v[220:223], v[128:131], v[64:79]
	v_add_f32_e32 v227, v165, v160
	v_add_f32_e32 v224, v156, v224
	v_add_f32_e32 v225, v158, v225
	v_add_f32_e32 v226, v155, v226
	ds_read_b128 v[216:219], v248 offset:24704
	ds_read_b128 v[220:223], v248 offset:36992
	s_waitcnt lgkmcnt(4)
	v_mfma_f32_32x32x16_bf16 v[80:95], v[232:235], v[124:127], v[80:95]
	v_add_f32_e32 v227, v157, v227
	v_add_f32_e32 v224, v152, v224
	v_add_f32_e32 v225, v154, v225
	v_mfma_f32_32x32x16_bf16 v[64:79], v[236:239], v[124:127], v[64:79]
	v_add_f32_e32 v226, v151, v226
	v_add_f32_e32 v227, v153, v227
	v_add_f32_e32 v224, v144, v224
	ds_read_b128 v[232:235], v249 offset:24704
	ds_read_b128 v[236:239], v249 offset:36992
	s_waitcnt lgkmcnt(4)
	v_mfma_f32_32x32x16_bf16 v[80:95], v[200:203], v[120:123], v[80:95]
	v_add_f32_e32 v225, v185, v225
	v_exp_f32_e32 v212, v179
	v_add_f32_e32 v226, v186, v226
	v_mfma_f32_32x32x16_bf16 v[64:79], v[204:207], v[120:123], v[64:79]
	v_add_f32_e32 v227, v187, v227
	v_add_f32_e32 v224, v188, v224
	v_add_f32_e32 v225, v189, v225
	ds_read_b128 v[200:203], v246 offset:24832
	ds_read_b128 v[204:207], v246 offset:37120
	s_waitcnt lgkmcnt(4)
	v_mfma_f32_32x32x16_bf16 v[80:95], v[216:219], v[116:119], v[80:95]
	v_add_f32_e32 v226, v212, v226
	v_add_f32_e32 v227, v180, v227
	v_exp_f32_e32 v213, v177
	v_mfma_f32_32x32x16_bf16 v[64:79], v[220:223], v[116:119], v[64:79]
	v_add_f32_e32 v224, v181, v224
	v_add_f32_e32 v225, v182, v225
	v_add_f32_e32 v226, v183, v226
	ds_read_b128 v[216:219], v247 offset:24832
	ds_read_b128 v[220:223], v247 offset:37120
	s_waitcnt lgkmcnt(4)
	v_mfma_f32_32x32x16_bf16 v[80:95], v[232:235], v[112:115], v[80:95]
	v_add_f32_e32 v227, v184, v227
	v_add_f32_e32 v224, v213, v224
	v_add_f32_e32 v225, v190, v225
	v_mfma_f32_32x32x16_bf16 v[64:79], v[236:239], v[112:115], v[64:79]
	v_add_f32_e32 v226, v191, v226
	v_add_f32_e32 v227, v214, v227
	v_add_f32_e32 v224, v224, v225
	v_add_f32_e32 v226, v226, v227
	v_add_f32_e32 v192, v224, v226
	v_mov_b32_e32 v193, v192
	s_nop 1
	ds_read_b128 v[232:235], v248 offset:24832
	ds_read_b128 v[236:239], v248 offset:37120
	s_waitcnt lgkmcnt(4)
	v_mfma_f32_32x32x16_bf16 v[80:95], v[200:203], v[108:111], v[80:95]
	v_permlane32_swap_b32_e32 v192, v193
	v_cvt_pk_bf16_f32 v176, v164, v172
	v_cvt_pk_bf16_f32 v177, v162, v165
	v_mfma_f32_32x32x16_bf16 v[64:79], v[204:207], v[108:111], v[64:79]
	v_cvt_pk_bf16_f32 v178, v161, v163
	v_cvt_pk_bf16_f32 v179, v159, v160
	v_cvt_pk_bf16_f32 v156, v156, v158
	ds_read_b128 v[200:203], v249 offset:24832
	ds_read_b128 v[204:207], v249 offset:37120
	s_waitcnt lgkmcnt(4)
	v_mfma_f32_32x32x16_bf16 v[80:95], v[216:219], v[104:107], v[80:95]
	v_cvt_pk_bf16_f32 v157, v155, v157
	v_cvt_pk_bf16_f32 v158, v152, v154
	v_cvt_pk_bf16_f32 v159, v151, v153
	v_mfma_f32_32x32x16_bf16 v[64:79], v[220:223], v[104:107], v[64:79]
	v_cvt_pk_bf16_f32 v152, v144, v185
	v_cvt_pk_bf16_f32 v153, v186, v187
	v_cvt_pk_bf16_f32 v154, v188, v189
	s_waitcnt lgkmcnt(2)
	v_mfma_f32_32x32x16_bf16 v[80:95], v[232:235], v[100:103], v[80:95]
	v_cvt_pk_bf16_f32 v155, v212, v180
	v_cvt_pk_bf16_f32 v160, v181, v182
	v_cvt_pk_bf16_f32 v161, v183, v184
	v_mfma_f32_32x32x16_bf16 v[64:79], v[236:239], v[100:103], v[64:79]
	v_cvt_pk_bf16_f32 v162, v213, v190
	v_cvt_pk_bf16_f32 v163, v191, v214
	v_permlane32_swap_b32_e32 v176, v178
	s_waitcnt lgkmcnt(0)
	v_mfma_f32_32x32x16_bf16 v[80:95], v[200:203], v[96:99], v[80:95]
	v_permlane32_swap_b32_e32 v177, v179
	v_permlane32_swap_b32_e32 v156, v158
	v_permlane32_swap_b32_e32 v157, v159
	v_mfma_f32_32x32x16_bf16 v[64:79], v[204:207], v[96:99], v[64:79]
	v_permlane32_swap_b32_e32 v152, v154
	v_permlane32_swap_b32_e32 v153, v155
	v_permlane32_swap_b32_e32 v160, v162
	v_permlane32_swap_b32_e32 v161, v163
	s_add_i32 s4, s48, s4
	v_add_u32_e32 v144, s4, v250
	ds_read_b64_tr_b16 v[180:181], v144 offset:0
	ds_read_b64_tr_b16 v[182:183], v144 offset:0x800
	ds_read_b64_tr_b16 v[184:185], v144 offset:0x1000
	ds_read_b64_tr_b16 v[186:187], v144 offset:0x1800
	ds_read_b64_tr_b16 v[188:189], v144 offset:0x2000
	ds_read_b64_tr_b16 v[190:191], v144 offset:0x2800
	ds_read_b64_tr_b16 v[194:195], v144 offset:0x3000
	ds_read_b64_tr_b16 v[196:197], v144 offset:0x3800
	s_waitcnt lgkmcnt(0)
	s_nop 0
	v_mfma_f32_32x32x16_bf16 v[0:15], v[176:179], v[180:183], v[0:15]
	ds_read_b64_tr_b16 v[180:181], v144 offset:0x200
	ds_read_b64_tr_b16 v[182:183], v144 offset:0xa00
	v_mfma_f32_32x32x16_bf16 v[0:15], v[156:159], v[184:187], v[0:15]
	ds_read_b64_tr_b16 v[184:185], v144 offset:0x1200
	ds_read_b64_tr_b16 v[186:187], v144 offset:0x1a00
	v_mfma_f32_32x32x16_bf16 v[0:15], v[152:155], v[188:191], v[0:15]
	ds_read_b64_tr_b16 v[188:189], v144 offset:0x2200
	ds_read_b64_tr_b16 v[190:191], v144 offset:0x2a00
	ds_read_b64_tr_b16 v[198:199], v144 offset:0x3200
	ds_read_b64_tr_b16 v[200:201], v144 offset:0x3a00
	s_waitcnt lgkmcnt(0)
	v_mfma_f32_32x32x16_bf16 v[0:15], v[160:163], v[194:197], v[0:15]
	v_mfma_f32_32x32x16_bf16 v[48:63], v[176:179], v[180:183], v[48:63]
	ds_read_b64_tr_b16 v[180:181], v144 offset:0x400
	ds_read_b64_tr_b16 v[182:183], v144 offset:0xc00
	v_mfma_f32_32x32x16_bf16 v[48:63], v[156:159], v[184:187], v[48:63]
	ds_read_b64_tr_b16 v[184:185], v144 offset:0x1400
	ds_read_b64_tr_b16 v[186:187], v144 offset:0x1c00
	v_mfma_f32_32x32x16_bf16 v[48:63], v[152:155], v[188:191], v[48:63]
	ds_read_b64_tr_b16 v[188:189], v144 offset:0x2400
	ds_read_b64_tr_b16 v[190:191], v144 offset:0x2c00
	ds_read_b64_tr_b16 v[194:195], v144 offset:0x3400
	ds_read_b64_tr_b16 v[196:197], v144 offset:0x3c00
	s_waitcnt lgkmcnt(0)
	v_mfma_f32_32x32x16_bf16 v[48:63], v[160:163], v[198:201], v[48:63]
	v_mfma_f32_32x32x16_bf16 v[32:47], v[176:179], v[180:183], v[32:47]
	ds_read_b64_tr_b16 v[180:181], v144 offset:0x600
	ds_read_b64_tr_b16 v[182:183], v144 offset:0xe00
	v_mfma_f32_32x32x16_bf16 v[32:47], v[156:159], v[184:187], v[32:47]
	ds_read_b64_tr_b16 v[184:185], v144 offset:0x1600
	ds_read_b64_tr_b16 v[186:187], v144 offset:0x1e00
	v_mfma_f32_32x32x16_bf16 v[32:47], v[152:155], v[188:191], v[32:47]
	ds_read_b64_tr_b16 v[188:189], v144 offset:0x2600
	ds_read_b64_tr_b16 v[190:191], v144 offset:0x2e00
	ds_read_b64_tr_b16 v[198:199], v144 offset:0x3600
	ds_read_b64_tr_b16 v[200:201], v144 offset:0x3e00
	s_waitcnt lgkmcnt(0)
	v_mfma_f32_32x32x16_bf16 v[32:47], v[160:163], v[194:197], v[32:47]
	v_mfma_f32_32x32x16_bf16 v[16:31], v[176:179], v[180:183], v[16:31]
	v_max_f32_e32 v144, v80, v81
	v_max3_f32 v144, v144, v82, v83
	v_max3_f32 v144, v144, v84, v85
	v_max3_f32 v144, v144, v86, v87
	v_max3_f32 v144, v144, v88, v89
	v_max3_f32 v144, v144, v90, v91
	v_mfma_f32_32x32x16_bf16 v[16:31], v[156:159], v[184:187], v[16:31]
	v_max3_f32 v144, v144, v92, v93
	v_max3_f32 v144, v144, v94, v95
	v_max3_f32 v144, v144, v64, v65
	v_max3_f32 v144, v144, v66, v67
	v_max3_f32 v144, v144, v68, v69
	v_max3_f32 v144, v144, v70, v71
	v_max3_f32 v144, v144, v72, v73
	v_max3_f32 v144, v144, v74, v75
	v_mfma_f32_32x32x16_bf16 v[16:31], v[152:155], v[188:191], v[16:31]
	v_max3_f32 v144, v144, v76, v77
	v_max3_f32 v144, v144, v78, v79
	v_mov_b32_e32 v151, v144
	s_nop 1
	v_permlane32_swap_b32_e32 v144, v151
	v_max_f32_e32 v144, v144, v151
	v_max_f32_e32 v151, v150, v144
	v_sub_f32_e32 v152, v144, v150
	v_mfma_f32_32x32x16_bf16 v[16:31], v[160:163], v[198:201], v[16:31]
	v_sub_f32_e32 v144, v150, v151
	v_mul_f32_e32 v144, 0x3dd53b94, v144
	v_exp_f32_e32 v144, v144
	v_cmp_ge_f32_e32 vcc, s63, v152
	s_cmp_eq_u64 vcc, exec
	s_cselect_b64 s[4:5], -1, 0
	s_waitcnt vmcnt(0)
	v_cndmask_b32_e64 v144, v144, 1.0, s[4:5]
	v_cmp_gt_f32_e32 vcc, 1.0, v144
	s_waitcnt vmcnt(0)
	s_barrier
	s_cbranch_vccz .LBB0_1106
	s_and_saveexec_b64 s[34:35], s[2:3]
	ds_write_b32 v149, v144 offset:128
	s_or_b64 exec, exec, s[34:35]
	s_waitcnt lgkmcnt(0)
	v_add_u32_e32 v164, v147, v148
	ds_read_b128 v[152:155], v164 offset:224
	ds_read_b128 v[156:159], v164 offset:192
	ds_read_b128 v[160:163], v164 offset:160
	ds_read_b128 v[176:179], v164 offset:128
	s_waitcnt lgkmcnt(3)
	v_pk_mul_f32 v[12:13], v[12:13], v[152:153]
	s_waitcnt lgkmcnt(2)
	v_pk_mul_f32 v[8:9], v[8:9], v[156:157]
	s_waitcnt lgkmcnt(1)
	v_pk_mul_f32 v[4:5], v[4:5], v[160:161]
	v_pk_mul_f32 v[14:15], v[14:15], v[154:155]
	v_pk_mul_f32 v[10:11], v[10:11], v[158:159]
	v_pk_mul_f32 v[6:7], v[6:7], v[162:163]
	s_waitcnt lgkmcnt(0)
	v_pk_mul_f32 v[2:3], v[2:3], v[178:179]
	v_pk_mul_f32 v[0:1], v[0:1], v[176:177]
	v_pk_mul_f32 v[60:61], v[60:61], v[152:153]
	v_pk_mul_f32 v[56:57], v[56:57], v[156:157]
	v_pk_mul_f32 v[52:53], v[52:53], v[160:161]
	v_pk_mul_f32 v[62:63], v[62:63], v[154:155]
	v_pk_mul_f32 v[58:59], v[58:59], v[158:159]
	v_pk_mul_f32 v[54:55], v[54:55], v[162:163]
	v_pk_mul_f32 v[50:51], v[50:51], v[178:179]
	v_pk_mul_f32 v[48:49], v[48:49], v[176:177]
	v_pk_mul_f32 v[44:45], v[44:45], v[152:153]
	v_pk_mul_f32 v[40:41], v[40:41], v[156:157]
	v_pk_mul_f32 v[36:37], v[36:37], v[160:161]
	v_pk_mul_f32 v[46:47], v[46:47], v[154:155]
	v_pk_mul_f32 v[42:43], v[42:43], v[158:159]
	v_pk_mul_f32 v[38:39], v[38:39], v[162:163]
	v_pk_mul_f32 v[34:35], v[34:35], v[178:179]
	v_pk_mul_f32 v[32:33], v[32:33], v[176:177]
	v_pk_mul_f32 v[28:29], v[28:29], v[152:153]
	v_pk_mul_f32 v[24:25], v[24:25], v[156:157]
	v_pk_mul_f32 v[20:21], v[20:21], v[160:161]
	v_pk_mul_f32 v[30:31], v[30:31], v[154:155]
	v_pk_mul_f32 v[26:27], v[26:27], v[158:159]
	v_pk_mul_f32 v[22:23], v[22:23], v[162:163]
	v_pk_mul_f32 v[18:19], v[18:19], v[178:179]
	v_pk_mul_f32 v[16:17], v[16:17], v[176:177]
.LBB0_1106:
	v_cndmask_b32_e64 v172, v151, v150, s[4:5]
	v_mul_f32_e32 v154, 0xbdd53b94, v172
	v_mov_b32_e32 v155, v154
	v_pk_fma_f32 v[162:163], v[64:65], s[18:19], v[154:155] op_sel_hi:[1,0,0]
	v_pk_fma_f32 v[160:161], v[66:67], s[18:19], v[154:155] op_sel_hi:[1,0,0]
	v_pk_fma_f32 v[156:157], v[68:69], s[18:19], v[154:155] op_sel_hi:[1,0,0]
	v_pk_fma_f32 v[152:153], v[70:71], s[18:19], v[154:155] op_sel_hi:[1,0,0]
	ds_read_b128 v[64:67], v246 offset:49152
	ds_read_b128 v[68:71], v246 offset:61440
	ds_read_b128 v[232:235], v247 offset:49152
	ds_read_b128 v[236:239], v247 offset:61440
	ds_read_b128 v[200:203], v248 offset:49152
	ds_read_b128 v[204:207], v248 offset:61440
	v_fmamk_f32 v80, v80, 0x3dd53b94, v154
	v_fmamk_f32 v81, v81, 0x3dd53b94, v154
	v_fmamk_f32 v82, v82, 0x3dd53b94, v154
	v_fmamk_f32 v83, v83, 0x3dd53b94, v154
	v_fmamk_f32 v84, v84, 0x3dd53b94, v154
	v_fmamk_f32 v85, v85, 0x3dd53b94, v154
	v_fmamk_f32 v86, v86, 0x3dd53b94, v154
	v_fmamk_f32 v87, v87, 0x3dd53b94, v154
	v_fmamk_f32 v88, v88, 0x3dd53b94, v154
	v_fmamk_f32 v89, v89, 0x3dd53b94, v154
	v_fmamk_f32 v90, v90, 0x3dd53b94, v154
	v_fmamk_f32 v91, v91, 0x3dd53b94, v154
	v_fmamk_f32 v92, v92, 0x3dd53b94, v154
	v_fmamk_f32 v93, v93, 0x3dd53b94, v154
	v_fmamk_f32 v94, v94, 0x3dd53b94, v154
	v_fmac_f32_e32 v155, 0x3dd53b94, v95
	s_add_u32 s41, s41, 0x8000
	v_exp_f32_e32 v185, v80
	v_exp_f32_e32 v189, v81
	v_exp_f32_e32 v186, v82
	v_exp_f32_e32 v190, v83
	v_exp_f32_e32 v187, v84
	v_exp_f32_e32 v191, v85
	v_exp_f32_e32 v184, v86
	v_exp_f32_e32 v188, v87
	v_exp_f32_e32 v178, v88
	v_exp_f32_e32 v182, v89
	v_exp_f32_e32 v179, v90
	v_exp_f32_e32 v183, v91
	v_exp_f32_e32 v176, v92
	v_exp_f32_e32 v180, v93
	v_exp_f32_e32 v177, v94
	v_exp_f32_e32 v181, v155
	s_addc_u32 s42, s42, 0
	v_add_f32_e32 v251, v173, v174
	s_add_u32 s43, s43, 0xc000
	v_fmac_f32_e32 v251, v171, v170
	v_add_f32_e32 v170, v192, v193
	s_addc_u32 s44, s44, 0
	s_add_i32 s78, s78, 2
	v_pk_fma_f32 v[150:151], v[72:73], s[18:19], v[154:155] op_sel_hi:[1,0,0]
	v_pk_fma_f32 v[164:165], v[74:75], s[18:19], v[154:155] op_sel_hi:[1,0,0]
	v_pk_fma_f32 v[158:159], v[76:77], s[18:19], v[154:155] op_sel_hi:[1,0,0]
	v_pk_fma_f32 v[154:155], v[78:79], s[18:19], v[154:155] op_sel_hi:[1,0,0]
	s_cmp_gt_u32 s78, 64
	v_fmac_f32_e32 v170, v251, v175
	s_cbranch_scc1 .LBB0_1108
	s_mov_b32 s36, s47
	s_mov_b32 s47, s48
	v_mov_b32_e32 v171, v144
	s_branch .LBB0_1098
.LBB0_1108:
	s_waitcnt lgkmcnt(0)
	v_mov_b32_e32 v64, v166
	v_exp_f32_e32 v162, v162
	v_lshlrev_b32_e32 v66, 3, v64
	v_and_b32_e32 v65, 31, v64
	v_and_b32_e32 v171, 0x70, v66
	v_mov_b32_e32 v66, s49
	v_lshrrev_b32_e32 v64, 1, v64
	v_mad_u32_u24 v173, v65, s54, v66
	v_and_b32_e32 v174, 16, v64
	v_xad_u32 v175, v174, v171, v173
	ds_read_b128 v[64:67], v175
	ds_read_b128 v[192:195], v175 offset:128
	ds_read_b128 v[80:83], v175 offset:12288
	ds_read_b128 v[196:199], v175 offset:256
	s_waitcnt lgkmcnt(3)
	v_mfma_f32_32x32x16_bf16 v[64:79], v[64:67], v[140:143], 0
	v_or_b32_e32 v84, 32, v174
	v_xad_u32 v216, v84, v171, v173
	v_or_b32_e32 v204, 64, v174
	v_xad_u32 v217, v204, v171, v173
	v_or_b32_e32 v174, 0x60, v174
	v_xad_u32 v171, v174, v171, v173
	v_exp_f32_e32 v163, v163
	s_waitcnt lgkmcnt(1)
	v_mfma_f32_32x32x16_bf16 v[80:95], v[80:83], v[140:143], 0
	ds_read_b128 v[140:143], v216
	ds_read_b128 v[200:203], v216 offset:128
	ds_read_b128 v[204:207], v216 offset:256
	v_exp_f32_e32 v160, v160
	v_exp_f32_e32 v161, v161
	v_exp_f32_e32 v156, v156
	s_waitcnt lgkmcnt(2)
	v_mfma_f32_32x32x16_bf16 v[64:79], v[140:143], v[136:139], v[64:79]
	ds_read_b128 v[140:143], v216 offset:12288
	s_waitcnt lgkmcnt(0)
	v_mfma_f32_32x32x16_bf16 v[80:95], v[140:143], v[136:139], v[80:95]
	ds_read_b128 v[136:139], v217
	ds_read_b128 v[140:143], v217 offset:128
	ds_read_b128 v[208:211], v217 offset:256
	s_waitcnt lgkmcnt(2)
	v_mfma_f32_32x32x16_bf16 v[64:79], v[136:139], v[132:135], v[64:79]
	ds_read_b128 v[136:139], v217 offset:12288
	s_waitcnt lgkmcnt(0)
	v_mfma_f32_32x32x16_bf16 v[80:95], v[136:139], v[132:135], v[80:95]
	ds_read_b128 v[132:135], v171
	ds_read_b128 v[136:139], v171 offset:128
	s_waitcnt lgkmcnt(1)
	v_mfma_f32_32x32x16_bf16 v[64:79], v[132:135], v[128:131], v[64:79]
	ds_read_b128 v[132:135], v171 offset:12288
	ds_read_b128 v[212:215], v171 offset:256
	s_waitcnt lgkmcnt(1)
	v_mfma_f32_32x32x16_bf16 v[80:95], v[132:135], v[128:131], v[80:95]
	ds_read_b128 v[128:131], v175 offset:12416
	ds_read_b128 v[132:135], v175 offset:12544
	v_mfma_f32_32x32x16_bf16 v[64:79], v[192:195], v[124:127], v[64:79]
	s_waitcnt lgkmcnt(1)
	v_mfma_f32_32x32x16_bf16 v[80:95], v[128:131], v[124:127], v[80:95]
	v_mfma_f32_32x32x16_bf16 v[64:79], v[200:203], v[120:123], v[64:79]
	ds_read_b128 v[124:127], v216 offset:12416
	ds_read_b128 v[128:131], v216 offset:12544
	ds_read_b128 v[192:195], v217 offset:12416
	ds_read_b128 v[200:203], v217 offset:12544
	s_waitcnt lgkmcnt(3)
	v_mfma_f32_32x32x16_bf16 v[80:95], v[124:127], v[120:123], v[80:95]
	ds_read_b128 v[120:123], v171 offset:12416
	ds_read_b128 v[124:127], v171 offset:12544
	v_mfma_f32_32x32x16_bf16 v[64:79], v[140:143], v[116:119], v[64:79]
	v_exp_f32_e32 v140, v157
	v_exp_f32_e32 v141, v152
	v_exp_f32_e32 v142, v153
	v_exp_f32_e32 v143, v150
	v_exp_f32_e32 v150, v151
	v_exp_f32_e32 v151, v164
	v_exp_f32_e32 v152, v165
	s_waitcnt lgkmcnt(3)
	v_mfma_f32_32x32x16_bf16 v[80:95], v[192:195], v[116:119], v[80:95]
	v_add_f32_e32 v116, 0, v185
	v_add_f32_e32 v116, v189, v116
	v_add_f32_e32 v116, v186, v116
	v_add_f32_e32 v116, v190, v116
	v_add_f32_e32 v116, v187, v116
	v_add_f32_e32 v116, v191, v116
	v_add_f32_e32 v116, v184, v116
	v_mfma_f32_32x32x16_bf16 v[64:79], v[136:139], v[112:115], v[64:79]
	v_add_f32_e32 v116, v188, v116
	v_add_f32_e32 v116, v178, v116
	v_add_f32_e32 v116, v182, v116
	v_exp_f32_e32 v118, v158
	v_exp_f32_e32 v119, v159
	v_exp_f32_e32 v153, v154
	v_exp_f32_e32 v154, v155
	s_waitcnt lgkmcnt(1)
	v_mfma_f32_32x32x16_bf16 v[80:95], v[120:123], v[112:115], v[80:95]
	v_add_f32_e32 v112, v179, v116
	v_add_f32_e32 v112, v183, v112
	v_add_f32_e32 v112, v176, v112
	v_add_f32_e32 v112, v180, v112
	v_add_f32_e32 v112, v177, v112
	v_add_f32_e32 v112, v181, v112
	v_add_f32_e32 v112, v162, v112
	v_mfma_f32_32x32x16_bf16 v[64:79], v[196:199], v[108:111], v[64:79]
	v_add_f32_e32 v112, v163, v112
	v_add_f32_e32 v112, v160, v112
	v_add_f32_e32 v112, v161, v112
	v_add_f32_e32 v112, v156, v112
	v_add_f32_e32 v112, v140, v112
	v_add_f32_e32 v112, v141, v112
	v_add_f32_e32 v112, v142, v112
	v_mfma_f32_32x32x16_bf16 v[80:95], v[132:135], v[108:111], v[80:95]
	v_add_f32_e32 v108, v143, v112
	v_add_f32_e32 v108, v150, v108
	v_add_f32_e32 v108, v151, v108
	v_add_f32_e32 v108, v152, v108
	v_add_f32_e32 v108, v118, v108
	v_add_f32_e32 v108, v119, v108
	v_add_f32_e32 v108, v153, v108
	v_mfma_f32_32x32x16_bf16 v[64:79], v[204:207], v[104:107], v[64:79]
	v_add_f32_e32 v108, v154, v108
	v_mov_b32_e32 v109, v108
	s_nop 1
	v_permlane32_swap_b32_e32 v108, v109
	v_cvt_pk_bf16_f32 v110, v185, v189
	v_cvt_pk_bf16_f32 v111, v186, v190
	v_cvt_pk_bf16_f32 v112, v187, v191
	v_mfma_f32_32x32x16_bf16 v[80:95], v[128:131], v[104:107], v[80:95]
	v_cvt_pk_bf16_f32 v113, v184, v188
	v_cvt_pk_bf16_f32 v104, v178, v182
	v_cvt_pk_bf16_f32 v105, v179, v183
	v_cvt_pk_bf16_f32 v106, v176, v180
	v_cvt_pk_bf16_f32 v107, v177, v181
	v_cvt_pk_bf16_f32 v114, v162, v163
	v_cvt_pk_bf16_f32 v115, v160, v161
	v_mfma_f32_32x32x16_bf16 v[64:79], v[208:211], v[100:103], v[64:79]
	v_cvt_pk_bf16_f32 v116, v156, v140
	v_cvt_pk_bf16_f32 v117, v141, v142
	v_permlane32_swap_b32_e32 v110, v112
	v_permlane32_swap_b32_e32 v111, v113
	v_permlane32_swap_b32_e32 v104, v106
	v_mfma_f32_32x32x16_bf16 v[80:95], v[200:203], v[100:103], v[80:95]
	v_cvt_pk_bf16_f32 v100, v143, v150
	v_cvt_pk_bf16_f32 v101, v151, v152
	v_cvt_pk_bf16_f32 v102, v118, v119
	v_cvt_pk_bf16_f32 v103, v153, v154
	v_permlane32_swap_b32_e32 v105, v107
	v_permlane32_swap_b32_e32 v114, v116
	v_mfma_f32_32x32x16_bf16 v[64:79], v[212:215], v[96:99], v[64:79]
	v_permlane32_swap_b32_e32 v115, v117
	v_permlane32_swap_b32_e32 v100, v102
	v_permlane32_swap_b32_e32 v101, v103
	s_waitcnt lgkmcnt(0)
	v_mfma_f32_32x32x16_bf16 v[80:95], v[124:127], v[96:99], v[80:95]
	v_mov_b32_e32 v96, v166
	s_cmp_lg_u32 0, -1
	v_lshlrev_b32_e32 v97, 3, v96
	v_lshlrev_b32_e32 v99, 4, v96
	v_lshlrev_b32_e32 v96, 1, v96
	v_and_b32_e32 v98, 24, v97
	v_and_b32_e32 v99, 0xc0, v99
	v_and_b32_e32 v96, 32, v96
	v_or3_b32 v96, v98, v99, v96
	v_and_b32_e32 v97, 0x100, v97
	s_cselect_b32 s0, 0, 0
	v_add3_u32 v134, v97, s0, v96
	ds_read_b64_tr_b16 v[96:97], v134 offset:0
	ds_read_b64_tr_b16 v[98:99], v134 offset:0x800
	ds_read_b64_tr_b16 v[118:119], v134 offset:0x1000
	ds_read_b64_tr_b16 v[120:121], v134 offset:0x1800
	ds_read_b64_tr_b16 v[122:123], v134 offset:0x2000
	ds_read_b64_tr_b16 v[124:125], v134 offset:0x2800
	ds_read_b64_tr_b16 v[126:127], v134 offset:0x3000
	ds_read_b64_tr_b16 v[128:129], v134 offset:0x3800
	s_waitcnt lgkmcnt(0)
	s_nop 0
	v_mfma_f32_32x32x16_bf16 v[0:15], v[110:113], v[96:99], v[0:15]
	ds_read_b64_tr_b16 v[96:97], v134 offset:0x200
	ds_read_b64_tr_b16 v[98:99], v134 offset:0xa00
	v_mfma_f32_32x32x16_bf16 v[0:15], v[104:107], v[118:121], v[0:15]
	ds_read_b64_tr_b16 v[118:119], v134 offset:0x1200
	ds_read_b64_tr_b16 v[120:121], v134 offset:0x1a00
	v_mfma_f32_32x32x16_bf16 v[0:15], v[114:117], v[122:125], v[0:15]
	ds_read_b64_tr_b16 v[122:123], v134 offset:0x2200
	ds_read_b64_tr_b16 v[124:125], v134 offset:0x2a00
	ds_read_b64_tr_b16 v[130:131], v134 offset:0x3200
	ds_read_b64_tr_b16 v[132:133], v134 offset:0x3a00
	s_waitcnt lgkmcnt(0)
	v_mfma_f32_32x32x16_bf16 v[0:15], v[100:103], v[126:129], v[0:15]
	v_mfma_f32_32x32x16_bf16 v[48:63], v[110:113], v[96:99], v[48:63]
	ds_read_b64_tr_b16 v[96:97], v134 offset:0x400
	ds_read_b64_tr_b16 v[98:99], v134 offset:0xc00
	v_mfma_f32_32x32x16_bf16 v[48:63], v[104:107], v[118:121], v[48:63]
	ds_read_b64_tr_b16 v[118:119], v134 offset:0x1400
	ds_read_b64_tr_b16 v[120:121], v134 offset:0x1c00
	v_mfma_f32_32x32x16_bf16 v[48:63], v[114:117], v[122:125], v[48:63]
	ds_read_b64_tr_b16 v[122:123], v134 offset:0x2400
	ds_read_b64_tr_b16 v[124:125], v134 offset:0x2c00
	ds_read_b64_tr_b16 v[126:127], v134 offset:0x3400
	ds_read_b64_tr_b16 v[128:129], v134 offset:0x3c00
	s_waitcnt lgkmcnt(0)
	v_mfma_f32_32x32x16_bf16 v[48:63], v[100:103], v[130:133], v[48:63]
	v_mfma_f32_32x32x16_bf16 v[32:47], v[110:113], v[96:99], v[32:47]
	ds_read_b64_tr_b16 v[96:97], v134 offset:0x600
	ds_read_b64_tr_b16 v[98:99], v134 offset:0xe00
	v_mfma_f32_32x32x16_bf16 v[32:47], v[104:107], v[118:121], v[32:47]
	ds_read_b64_tr_b16 v[118:119], v134 offset:0x1600
	ds_read_b64_tr_b16 v[120:121], v134 offset:0x1e00
	v_mfma_f32_32x32x16_bf16 v[32:47], v[114:117], v[122:125], v[32:47]
	ds_read_b64_tr_b16 v[122:123], v134 offset:0x2600
	ds_read_b64_tr_b16 v[124:125], v134 offset:0x2e00
	ds_read_b64_tr_b16 v[130:131], v134 offset:0x3600
	ds_read_b64_tr_b16 v[132:133], v134 offset:0x3e00
	s_waitcnt lgkmcnt(0)
	v_mfma_f32_32x32x16_bf16 v[32:47], v[100:103], v[126:129], v[32:47]
	v_mfma_f32_32x32x16_bf16 v[16:31], v[110:113], v[96:99], v[16:31]
	v_max_f32_e32 v126, v65, v65
	v_max_f32_e32 v127, v64, v64
	v_max_f32_e32 v126, v127, v126
	v_max3_f32 v126, v126, v66, v67
	v_max3_f32 v126, v126, v68, v69
	v_max3_f32 v96, v126, v70, v71
	v_max3_f32 v96, v96, v72, v73
	v_max3_f32 v96, v96, v74, v75
	v_mfma_f32_32x32x16_bf16 v[16:31], v[104:107], v[118:121], v[16:31]
	v_max3_f32 v96, v96, v76, v77
	v_max3_f32 v96, v96, v78, v79
	v_max3_f32 v96, v96, v80, v81
	v_max3_f32 v96, v96, v82, v83
	v_max3_f32 v96, v96, v84, v85
	v_max3_f32 v96, v96, v86, v87
	v_max3_f32 v96, v96, v88, v89
	v_max3_f32 v96, v96, v90, v91
	v_mfma_f32_32x32x16_bf16 v[16:31], v[114:117], v[122:125], v[16:31]
	v_max3_f32 v96, v96, v92, v93
	v_max3_f32 v96, v96, v94, v95
	v_mov_b32_e32 v97, v96
	s_nop 1
	v_permlane32_swap_b32_e32 v96, v97
	v_max_f32_e32 v97, v97, v97
	v_max_f32_e32 v96, v96, v96
	v_max_f32_e32 v96, v96, v97
	v_max_f32_e32 v97, v172, v172
	v_max_f32_e32 v97, v97, v96
	v_sub_f32_e32 v98, v96, v172
	v_mfma_f32_32x32x16_bf16 v[16:31], v[100:103], v[130:133], v[16:31]
	v_sub_f32_e32 v96, v172, v97
	v_mul_f32_e32 v96, 0x3dd53b94, v96
	v_exp_f32_e32 v96, v96
	v_cmp_ge_f32_e32 vcc, s63, v98
	s_cmp_eq_u64 vcc, exec
	s_cselect_b64 s[4:5], -1, 0
	v_cndmask_b32_e64 v96, v96, 1.0, s[4:5]
	v_cmp_gt_f32_e32 vcc, 1.0, v96
	s_cbranch_vccz .LBB0_1112
	s_and_saveexec_b64 s[34:35], s[2:3]
	ds_write_b32 v149, v96 offset:128
	s_or_b64 exec, exec, s[34:35]
	s_waitcnt lgkmcnt(0)
	v_add_u32_e32 v106, v147, v148
	ds_read_b128 v[98:101], v106 offset:224
	ds_read_b128 v[102:105], v106 offset:192
	ds_read_b128 v[110:113], v106 offset:160
	ds_read_b128 v[114:117], v106 offset:128
	s_waitcnt lgkmcnt(3)
	v_pk_mul_f32 v[12:13], v[12:13], v[98:99]
	s_waitcnt lgkmcnt(2)
	v_pk_mul_f32 v[8:9], v[8:9], v[102:103]
	s_waitcnt lgkmcnt(1)
	v_pk_mul_f32 v[4:5], v[4:5], v[110:111]
	v_pk_mul_f32 v[14:15], v[14:15], v[100:101]
	v_pk_mul_f32 v[10:11], v[10:11], v[104:105]
	v_pk_mul_f32 v[6:7], v[6:7], v[112:113]
	s_waitcnt lgkmcnt(0)
	v_pk_mul_f32 v[2:3], v[2:3], v[116:117]
	v_pk_mul_f32 v[0:1], v[0:1], v[114:115]
	v_pk_mul_f32 v[60:61], v[60:61], v[98:99]
	v_pk_mul_f32 v[56:57], v[56:57], v[102:103]
	v_pk_mul_f32 v[52:53], v[52:53], v[110:111]
	v_pk_mul_f32 v[62:63], v[62:63], v[100:101]
	v_pk_mul_f32 v[58:59], v[58:59], v[104:105]
	v_pk_mul_f32 v[54:55], v[54:55], v[112:113]
	v_pk_mul_f32 v[50:51], v[50:51], v[116:117]
	v_pk_mul_f32 v[48:49], v[48:49], v[114:115]
	v_pk_mul_f32 v[44:45], v[44:45], v[98:99]
	v_pk_mul_f32 v[40:41], v[40:41], v[102:103]
	v_pk_mul_f32 v[36:37], v[36:37], v[110:111]
	v_pk_mul_f32 v[46:47], v[46:47], v[100:101]
	v_pk_mul_f32 v[42:43], v[42:43], v[104:105]
	v_pk_mul_f32 v[38:39], v[38:39], v[112:113]
	v_pk_mul_f32 v[34:35], v[34:35], v[116:117]
	v_pk_mul_f32 v[32:33], v[32:33], v[114:115]
	v_pk_mul_f32 v[28:29], v[28:29], v[98:99]
	v_pk_mul_f32 v[24:25], v[24:25], v[102:103]
	v_pk_mul_f32 v[20:21], v[20:21], v[110:111]
	v_pk_mul_f32 v[30:31], v[30:31], v[100:101]
	v_pk_mul_f32 v[26:27], v[26:27], v[104:105]
	v_pk_mul_f32 v[22:23], v[22:23], v[112:113]
	v_pk_mul_f32 v[18:19], v[18:19], v[116:117]
	v_pk_mul_f32 v[16:17], v[16:17], v[114:115]
